# scanner: reduce reads issued together with two waits, token base kept incrementally, prefetch reads used as the wait states around DPP ops in the first step of a group
# baseline (speedup 1.0000x reference)
; __device__ __forceinline__ void phase_rwkv_scan(const Fr& F, int jr) {
;     ...
;                 float* Ypw = Yp + wave * 1024;
;                 unsigned a1 = (unsigned)(size_t)(__attribute__((address_space(3))) float*)(Wv + ks), a2 = (unsigned)(size_t)(__attribute__((address_space(3))) float*)(Rr + ks),
;                          a3 = (unsigned)(size_t)(__attribute__((address_space(3))) float*)(Vv + rloc), a4 = (unsigned)(size_t)(__attribute__((address_space(3))) float*)(Ypw + lane);
;                 asm volatile("" : "+v"(a1), "+v"(a2), "+v"(a3), "+v"(a4));
;                 typedef const __attribute__((address_space(3))) f32x4* lp4; typedef const __attribute__((address_space(3))) float* lp1; typedef __attribute__((address_space(3))) float* lw1;
;                 const lp4 PW = (lp4)a1, PR = (lp4)a2; const lp1 PV = (lp1)a3; const lw1 PY = (lw1)a4;
;                 f32x4 w4 = PW[0], k4 = PW[1024], b4 = PW[2048], d4 = PW[3072], r4 = PR[0];
;                 float vv = PV[0];
;                 for (int pg = 0; pg < 64; pg += 16) {
; #pragma unroll
;                     for (int pi = 0; pi < 16; ++pi) {
;                         const int p = pg + pi, pn = p < 63 ? p + 1 : 63;
;                         const f32x4 w4n = PW[pn * 16], k4n = PW[1024 + pn * 16], b4n = PW[2048 + pn * 16], d4n = PW[3072 + pn * 16], r4n = PR[pn * 16];
;                         const float vvn = PV[pn * 32];
;                         f32x2 t = S01 * k4.xy; t = S23 * k4.zw + t; float sa = t.x + t.y;
;                         sa += dppf<0x128>(sa);
;                         const f32x2 dv01 = d4.xy * vv, dv23 = d4.zw * vv;
;                         sa += dppf<0x124>(sa);
;                         const f32x2 e01 = S01 * w4.xy + dv01;
;                         sa += dppf<0x122>(sa);
;                         const f32x2 e23 = S23 * w4.zw + dv23;
;                         sa += dppf<0x121>(sa);
;                         S01 = e01 - b4.xy * sa; S23 = e23 - b4.zw * sa;
;                         f32x2 u = S01 * r4.xy; u = S23 * r4.zw + u;
;                         PY[pi * 64] = u.x + u.y;
;                         w4 = w4n; k4 = k4n; b4 = b4n; d4 = d4n; r4 = r4n; vv = vvn;
;     ...
;                         const size_t row = (size_t)b * TB + tokof(s, chunk * 64 + pg + j);
;                         Yb[row * D + h * 64 + 32 * half + 4 * wave + q] = (bf16)f2bf(yv);
.Lrw0_sdir0:
	v_and_b32_e32 v243, 3, v130
	s_lshl_b32 s16, s68, 4
	v_lshl_add_u32 v220, v243, 2, s16
	s_mul_i32 s16, s6, 0x2200000
	s_add_u32 s20, s26, s16
	s_addc_u32 s21, s27, 0
	s_add_u32 s20, s20, 0x1200000
	s_addc_u32 s21, s21, 0
	s_mul_i32 s16, s7, 0x880000
	s_add_u32 s20, s20, s16
	s_addc_u32 s21, s21, 0
	s_and_b32 s16, s3, 31
	s_lshl_b32 s16, s16, 6
	s_add_u32 s20, s20, s16
	s_addc_u32 s21, s21, 0
	s_mov_b32 s10, 0
	s_mov_b32 s11, 0
	s_cmp_eq_u32 s6, 0
	s_cselect_b32 s15, 0, 0xff
	s_cselect_b32 s19, 16, -16
	s_cselect_b32 s18, 0, 0x1100
	s_waitcnt lgkmcnt(0)
	s_barrier
.Lrw0_shc:
	v_add_u32_e32 v240, s11, v214
	v_add_u32_e32 v242, s11, v216
	ds_read_b128 v[84:87], v240 offset:8704
	ds_read_b128 v[56:59], v242 offset:43520
	ds_read_b128 v[92:95], v240 offset:26112
	ds_read_b128 v[80:83], v240 offset:0
	ds_read_b128 v[88:91], v240 offset:17408
	ds_read_b128 v[96:99], v240 offset:34816
	ds_read_b128 v[106:109], v240 offset:8976
	ds_read_b128 v[114:117], v240 offset:26384
	ds_read_b128 v[102:105], v240 offset:272
	ds_read_b128 v[110:113], v240 offset:17680
	s_waitcnt lgkmcnt(5)
	ds_read_b128 v[4:7], v240 offset:9248
	ds_read_b128 v[60:63], v242 offset:44048
	v_pk_mul_f32 v[226:227], v[206:207], v[84:85] op_sel_hi:[1,0]
	v_pk_mul_f32 v[232:233], v[56:57], v[92:93] op_sel_hi:[1,0]
	v_pk_fma_f32 v[226:227], v[208:209], v[84:85], v[226:227] op_sel:[0,1,0]
	v_pk_mul_f32 v[234:235], v[56:57], v[92:93] op_sel:[0,1]
	v_pk_fma_f32 v[226:227], v[210:211], v[86:87], v[226:227] op_sel_hi:[1,0,1]
	v_pk_mul_f32 v[236:237], v[56:57], v[94:95] op_sel_hi:[1,0]
	v_pk_fma_f32 v[226:227], v[212:213], v[86:87], v[226:227] op_sel:[0,1,0]
	v_pk_mul_f32 v[238:239], v[56:57], v[94:95] op_sel:[0,1]
	ds_read_b128 v[12:15], v240 offset:26656
	v_add_f32_dpp v230, v227, v226 row_ror:8 row_mask:0xf bank_mask:0xf
	v_pk_fma_f32 v[232:233], v[206:207], v[80:81], v[232:233] op_sel_hi:[1,0,1]
	v_pk_fma_f32 v[234:235], v[208:209], v[80:81], v[234:235] op_sel:[0,1,0]
	v_add_f32_dpp v230, v230, v230 quad_perm:[1,0,3,2] row_mask:0xf bank_mask:0xf
	v_pk_fma_f32 v[236:237], v[210:211], v[82:83], v[236:237] op_sel_hi:[1,0,1]
	v_pk_fma_f32 v[238:239], v[212:213], v[82:83], v[238:239] op_sel:[0,1,0]
	v_add_f32_dpp v230, v230, v230 quad_perm:[2,3,0,1] row_mask:0xf bank_mask:0xf
	ds_read_b128 v[222:225], v240 offset:35088
	ds_read_b128 v[0:3], v240 offset:544
	v_add_f32_dpp v230, v230, v230 row_half_mirror row_mask:0xf bank_mask:0xf
	ds_read_b128 v[8:11], v240 offset:17952
	s_nop 0
	v_mov_b32_dpp v231, v230 row_ror:8 row_mask:0xf bank_mask:0xf
	v_pk_fma_f32 v[206:207], v[88:89], v[230:231], v[232:233] op_sel_hi:[0,1,1] neg_lo:[1,0,0] neg_hi:[1,0,0]
	v_pk_fma_f32 v[208:209], v[88:89], v[230:231], v[234:235] op_sel:[1,0,0] neg_lo:[1,0,0] neg_hi:[1,0,0]
	v_pk_fma_f32 v[210:211], v[90:91], v[230:231], v[236:237] op_sel_hi:[0,1,1] neg_lo:[1,0,0] neg_hi:[1,0,0]
	v_pk_fma_f32 v[212:213], v[90:91], v[230:231], v[238:239] op_sel:[1,0,0] neg_lo:[1,0,0] neg_hi:[1,0,0]
	s_waitcnt lgkmcnt(6)
	ds_read_b128 v[84:87], v240 offset:9520
	ds_read_b128 v[92:95], v240 offset:26928
	ds_read_b128 v[80:83], v240 offset:816
	ds_read_b128 v[88:91], v240 offset:18224
	v_pk_mul_f32 v[226:227], v[206:207], v[106:107] op_sel_hi:[1,0]
	v_pk_mul_f32 v[228:229], v[206:207], v[96:97] op_sel_hi:[1,0]
	v_pk_fma_f32 v[226:227], v[208:209], v[106:107], v[226:227] op_sel:[0,1,0]
	v_pk_fma_f32 v[228:229], v[208:209], v[96:97], v[228:229] op_sel:[0,1,0]
	v_pk_fma_f32 v[226:227], v[210:211], v[108:109], v[226:227] op_sel_hi:[1,0,1]
	v_pk_fma_f32 v[228:229], v[210:211], v[98:99], v[228:229] op_sel_hi:[1,0,1]
	v_pk_fma_f32 v[226:227], v[212:213], v[108:109], v[226:227] op_sel:[0,1,0]
	v_pk_fma_f32 v[228:229], v[212:213], v[98:99], v[228:229] op_sel:[0,1,0]
	v_pk_mul_f32 v[232:233], v[58:59], v[114:115] op_sel_hi:[1,0]
	v_add_f32_dpp v230, v227, v226 row_ror:8 row_mask:0xf bank_mask:0xf
	v_pk_mul_f32 v[234:235], v[58:59], v[114:115] op_sel:[0,1]
	v_pk_mul_f32 v[236:237], v[58:59], v[116:117] op_sel_hi:[1,0]
	v_add_f32_dpp v230, v230, v230 quad_perm:[1,0,3,2] row_mask:0xf bank_mask:0xf
	v_pk_mul_f32 v[238:239], v[58:59], v[116:117] op_sel:[0,1]
	ds_read_b128 v[96:99], v240 offset:35360
	v_add_f32_dpp v230, v230, v230 quad_perm:[2,3,0,1] row_mask:0xf bank_mask:0xf
	v_pk_fma_f32 v[232:233], v[206:207], v[102:103], v[232:233] op_sel_hi:[1,0,1]
	v_pk_fma_f32 v[234:235], v[208:209], v[102:103], v[234:235] op_sel:[0,1,0]
	v_add_f32_dpp v230, v230, v230 row_half_mirror row_mask:0xf bank_mask:0xf
	v_pk_fma_f32 v[236:237], v[210:211], v[104:105], v[236:237] op_sel_hi:[1,0,1]
	v_pk_fma_f32 v[238:239], v[212:213], v[104:105], v[238:239] op_sel:[0,1,0]
	v_mov_b32_dpp v231, v230 row_ror:8 row_mask:0xf bank_mask:0xf
	ds_write_b64 v217, v[228:229] offset:0
	v_pk_fma_f32 v[206:207], v[110:111], v[230:231], v[232:233] op_sel_hi:[0,1,1] neg_lo:[1,0,0] neg_hi:[1,0,0]
	v_pk_fma_f32 v[208:209], v[110:111], v[230:231], v[234:235] op_sel:[1,0,0] neg_lo:[1,0,0] neg_hi:[1,0,0]
	v_pk_fma_f32 v[210:211], v[112:113], v[230:231], v[236:237] op_sel_hi:[0,1,1] neg_lo:[1,0,0] neg_hi:[1,0,0]
	v_pk_fma_f32 v[212:213], v[112:113], v[230:231], v[238:239] op_sel:[1,0,0] neg_lo:[1,0,0] neg_hi:[1,0,0]
	s_waitcnt lgkmcnt(6)
; template <int CTRL> __device__ __forceinline__ float dppf(float x) { return __builtin_bit_cast(float, __builtin_amdgcn_update_dpp(0, __builtin_bit_cast(int, x), CTRL, 0xF, 0xF, false)); }
; __device__ __forceinline__ void phase_rwkv_scan(const Fr& F, int jr) {
;     ...
;                         const int p = pg + pi, pn = p < 63 ? p + 1 : 63;
;                         const f32x4 w4n = PW[pn * 16], k4n = PW[1024 + pn * 16], b4n = PW[2048 + pn * 16], d4n = PW[3072 + pn * 16], r4n = PR[pn * 16];
;                         const float vvn = PV[pn * 32];
;                         f32x2 t = S01 * k4.xy; t = S23 * k4.zw + t; float sa = t.x + t.y;
;                         sa += dppf<0x128>(sa);
;                         const f32x2 dv01 = d4.xy * vv, dv23 = d4.zw * vv;
;                         sa += dppf<0x124>(sa);
;                         const f32x2 e01 = S01 * w4.xy + dv01;
;                         sa += dppf<0x122>(sa);
;                         const f32x2 e23 = S23 * w4.zw + dv23;
;                         sa += dppf<0x121>(sa);
;                         S01 = e01 - b4.xy * sa; S23 = e23 - b4.zw * sa;
;                         f32x2 u = S01 * r4.xy; u = S23 * r4.zw + u;
;                         PY[pi * 64] = u.x + u.y;
;                         w4 = w4n; k4 = k4n; b4 = b4n; d4 = d4n; r4 = r4n; vv = vvn;
	ds_read_b128 v[106:109], v240 offset:9792
	ds_read_b128 v[56:59], v242 offset:44576
	ds_read_b128 v[114:117], v240 offset:27200
	ds_read_b128 v[102:105], v240 offset:1088
	ds_read_b128 v[110:113], v240 offset:18496
	v_pk_mul_f32 v[226:227], v[206:207], v[4:5] op_sel_hi:[1,0]
	v_pk_mul_f32 v[228:229], v[206:207], v[222:223] op_sel_hi:[1,0]
	v_pk_fma_f32 v[226:227], v[208:209], v[4:5], v[226:227] op_sel:[0,1,0]
	v_pk_fma_f32 v[228:229], v[208:209], v[222:223], v[228:229] op_sel:[0,1,0]
	v_pk_fma_f32 v[226:227], v[210:211], v[6:7], v[226:227] op_sel_hi:[1,0,1]
	v_pk_fma_f32 v[228:229], v[210:211], v[224:225], v[228:229] op_sel_hi:[1,0,1]
	v_pk_fma_f32 v[226:227], v[212:213], v[6:7], v[226:227] op_sel:[0,1,0]
	v_pk_fma_f32 v[228:229], v[212:213], v[224:225], v[228:229] op_sel:[0,1,0]
	v_pk_mul_f32 v[232:233], v[60:61], v[12:13] op_sel_hi:[1,0]
	v_add_f32_dpp v230, v227, v226 row_ror:8 row_mask:0xf bank_mask:0xf
	v_pk_mul_f32 v[234:235], v[60:61], v[12:13] op_sel:[0,1]
	v_pk_mul_f32 v[236:237], v[60:61], v[14:15] op_sel_hi:[1,0]
	v_add_f32_dpp v230, v230, v230 quad_perm:[1,0,3,2] row_mask:0xf bank_mask:0xf
	v_pk_mul_f32 v[238:239], v[60:61], v[14:15] op_sel:[0,1]
	ds_read_b128 v[222:225], v240 offset:35632
	v_add_f32_dpp v230, v230, v230 quad_perm:[2,3,0,1] row_mask:0xf bank_mask:0xf
	v_pk_fma_f32 v[232:233], v[206:207], v[0:1], v[232:233] op_sel_hi:[1,0,1]
	v_pk_fma_f32 v[234:235], v[208:209], v[0:1], v[234:235] op_sel:[0,1,0]
	v_add_f32_dpp v230, v230, v230 row_half_mirror row_mask:0xf bank_mask:0xf
	v_pk_fma_f32 v[236:237], v[210:211], v[2:3], v[236:237] op_sel_hi:[1,0,1]
	v_pk_fma_f32 v[238:239], v[212:213], v[2:3], v[238:239] op_sel:[0,1,0]
	v_mov_b32_dpp v231, v230 row_ror:8 row_mask:0xf bank_mask:0xf
	ds_write_b64 v217, v[228:229] offset:576
	v_pk_fma_f32 v[206:207], v[8:9], v[230:231], v[232:233] op_sel_hi:[0,1,1] neg_lo:[1,0,0] neg_hi:[1,0,0]
	v_pk_fma_f32 v[208:209], v[8:9], v[230:231], v[234:235] op_sel:[1,0,0] neg_lo:[1,0,0] neg_hi:[1,0,0]
	v_pk_fma_f32 v[210:211], v[10:11], v[230:231], v[236:237] op_sel_hi:[0,1,1] neg_lo:[1,0,0] neg_hi:[1,0,0]
	v_pk_fma_f32 v[212:213], v[10:11], v[230:231], v[238:239] op_sel:[1,0,0] neg_lo:[1,0,0] neg_hi:[1,0,0]
	s_waitcnt lgkmcnt(8)
	ds_read_b128 v[4:7], v240 offset:10064
	ds_read_b128 v[12:15], v240 offset:27472
	ds_read_b128 v[0:3], v240 offset:1360
	ds_read_b128 v[8:11], v240 offset:18768
	v_pk_mul_f32 v[226:227], v[206:207], v[84:85] op_sel_hi:[1,0]
	v_pk_mul_f32 v[228:229], v[206:207], v[96:97] op_sel_hi:[1,0]
	v_pk_fma_f32 v[226:227], v[208:209], v[84:85], v[226:227] op_sel:[0,1,0]
	v_pk_fma_f32 v[228:229], v[208:209], v[96:97], v[228:229] op_sel:[0,1,0]
	v_pk_fma_f32 v[226:227], v[210:211], v[86:87], v[226:227] op_sel_hi:[1,0,1]
	v_pk_fma_f32 v[228:229], v[210:211], v[98:99], v[228:229] op_sel_hi:[1,0,1]
	v_pk_fma_f32 v[226:227], v[212:213], v[86:87], v[226:227] op_sel:[0,1,0]
	v_pk_fma_f32 v[228:229], v[212:213], v[98:99], v[228:229] op_sel:[0,1,0]
	v_pk_mul_f32 v[232:233], v[62:63], v[92:93] op_sel_hi:[1,0]
	v_add_f32_dpp v230, v227, v226 row_ror:8 row_mask:0xf bank_mask:0xf
	v_pk_mul_f32 v[234:235], v[62:63], v[92:93] op_sel:[0,1]
	v_pk_mul_f32 v[236:237], v[62:63], v[94:95] op_sel_hi:[1,0]
	v_add_f32_dpp v230, v230, v230 quad_perm:[1,0,3,2] row_mask:0xf bank_mask:0xf
	v_pk_mul_f32 v[238:239], v[62:63], v[94:95] op_sel:[0,1]
	ds_read_b128 v[96:99], v240 offset:35904
	v_add_f32_dpp v230, v230, v230 quad_perm:[2,3,0,1] row_mask:0xf bank_mask:0xf
	v_pk_fma_f32 v[232:233], v[206:207], v[80:81], v[232:233] op_sel_hi:[1,0,1]
	v_pk_fma_f32 v[234:235], v[208:209], v[80:81], v[234:235] op_sel:[0,1,0]
	v_add_f32_dpp v230, v230, v230 row_half_mirror row_mask:0xf bank_mask:0xf
	v_pk_fma_f32 v[236:237], v[210:211], v[82:83], v[236:237] op_sel_hi:[1,0,1]
	v_pk_fma_f32 v[238:239], v[212:213], v[82:83], v[238:239] op_sel:[0,1,0]
	v_mov_b32_dpp v231, v230 row_ror:8 row_mask:0xf bank_mask:0xf
	ds_write_b64 v217, v[228:229] offset:1152
	v_pk_fma_f32 v[206:207], v[88:89], v[230:231], v[232:233] op_sel_hi:[0,1,1] neg_lo:[1,0,0] neg_hi:[1,0,0]
	v_pk_fma_f32 v[208:209], v[88:89], v[230:231], v[234:235] op_sel:[1,0,0] neg_lo:[1,0,0] neg_hi:[1,0,0]
	v_pk_fma_f32 v[210:211], v[90:91], v[230:231], v[236:237] op_sel_hi:[0,1,1] neg_lo:[1,0,0] neg_hi:[1,0,0]
	v_pk_fma_f32 v[212:213], v[90:91], v[230:231], v[238:239] op_sel:[1,0,0] neg_lo:[1,0,0] neg_hi:[1,0,0]
	s_waitcnt lgkmcnt(7)
	ds_read_b128 v[84:87], v240 offset:10336
	ds_read_b128 v[60:63], v242 offset:45104
	ds_read_b128 v[92:95], v240 offset:27744
	ds_read_b128 v[80:83], v240 offset:1632
	ds_read_b128 v[88:91], v240 offset:19040
	v_pk_mul_f32 v[226:227], v[206:207], v[106:107] op_sel_hi:[1,0]
	v_pk_mul_f32 v[228:229], v[206:207], v[222:223] op_sel_hi:[1,0]
	v_pk_fma_f32 v[226:227], v[208:209], v[106:107], v[226:227] op_sel:[0,1,0]
	v_pk_fma_f32 v[228:229], v[208:209], v[222:223], v[228:229] op_sel:[0,1,0]
	v_pk_fma_f32 v[226:227], v[210:211], v[108:109], v[226:227] op_sel_hi:[1,0,1]
	v_pk_fma_f32 v[228:229], v[210:211], v[224:225], v[228:229] op_sel_hi:[1,0,1]
	v_pk_fma_f32 v[226:227], v[212:213], v[108:109], v[226:227] op_sel:[0,1,0]
	v_pk_fma_f32 v[228:229], v[212:213], v[224:225], v[228:229] op_sel:[0,1,0]
	v_pk_mul_f32 v[232:233], v[56:57], v[114:115] op_sel_hi:[1,0]
	v_add_f32_dpp v230, v227, v226 row_ror:8 row_mask:0xf bank_mask:0xf
	v_pk_mul_f32 v[234:235], v[56:57], v[114:115] op_sel:[0,1]
	v_pk_mul_f32 v[236:237], v[56:57], v[116:117] op_sel_hi:[1,0]
	v_add_f32_dpp v230, v230, v230 quad_perm:[1,0,3,2] row_mask:0xf bank_mask:0xf
	v_pk_mul_f32 v[238:239], v[56:57], v[116:117] op_sel:[0,1]
	ds_read_b128 v[222:225], v240 offset:36176
	v_add_f32_dpp v230, v230, v230 quad_perm:[2,3,0,1] row_mask:0xf bank_mask:0xf
	v_pk_fma_f32 v[232:233], v[206:207], v[102:103], v[232:233] op_sel_hi:[1,0,1]
	v_pk_fma_f32 v[234:235], v[208:209], v[102:103], v[234:235] op_sel:[0,1,0]
	v_add_f32_dpp v230, v230, v230 row_half_mirror row_mask:0xf bank_mask:0xf
	v_pk_fma_f32 v[236:237], v[210:211], v[104:105], v[236:237] op_sel_hi:[1,0,1]
	v_pk_fma_f32 v[238:239], v[212:213], v[104:105], v[238:239] op_sel:[0,1,0]
	v_mov_b32_dpp v231, v230 row_ror:8 row_mask:0xf bank_mask:0xf
	ds_write_b64 v217, v[228:229] offset:1728
	v_pk_fma_f32 v[206:207], v[110:111], v[230:231], v[232:233] op_sel_hi:[0,1,1] neg_lo:[1,0,0] neg_hi:[1,0,0]
	v_pk_fma_f32 v[208:209], v[110:111], v[230:231], v[234:235] op_sel:[1,0,0] neg_lo:[1,0,0] neg_hi:[1,0,0]
	v_pk_fma_f32 v[210:211], v[112:113], v[230:231], v[236:237] op_sel_hi:[0,1,1] neg_lo:[1,0,0] neg_hi:[1,0,0]
	v_pk_fma_f32 v[212:213], v[112:113], v[230:231], v[238:239] op_sel:[1,0,0] neg_lo:[1,0,0] neg_hi:[1,0,0]
	s_waitcnt lgkmcnt(8)
; template <int CTRL> __device__ __forceinline__ float dppf(float x) { return __builtin_bit_cast(float, __builtin_amdgcn_update_dpp(0, __builtin_bit_cast(int, x), CTRL, 0xF, 0xF, false)); }
; __device__ __forceinline__ void phase_rwkv_scan(const Fr& F, int jr) {
;     ...
;                         const int p = pg + pi, pn = p < 63 ? p + 1 : 63;
;                         const f32x4 w4n = PW[pn * 16], k4n = PW[1024 + pn * 16], b4n = PW[2048 + pn * 16], d4n = PW[3072 + pn * 16], r4n = PR[pn * 16];
;                         const float vvn = PV[pn * 32];
;                         f32x2 t = S01 * k4.xy; t = S23 * k4.zw + t; float sa = t.x + t.y;
;                         sa += dppf<0x128>(sa);
;                         const f32x2 dv01 = d4.xy * vv, dv23 = d4.zw * vv;
;                         sa += dppf<0x124>(sa);
;                         const f32x2 e01 = S01 * w4.xy + dv01;
;                         sa += dppf<0x122>(sa);
;                         const f32x2 e23 = S23 * w4.zw + dv23;
;                         sa += dppf<0x121>(sa);
;                         S01 = e01 - b4.xy * sa; S23 = e23 - b4.zw * sa;
;                         f32x2 u = S01 * r4.xy; u = S23 * r4.zw + u;
;                         PY[pi * 64] = u.x + u.y;
;                         w4 = w4n; k4 = k4n; b4 = b4n; d4 = d4n; r4 = r4n; vv = vvn;
	ds_read_b128 v[106:109], v240 offset:10608
	ds_read_b128 v[114:117], v240 offset:28016
	ds_read_b128 v[102:105], v240 offset:1904
	ds_read_b128 v[110:113], v240 offset:19312
	v_pk_mul_f32 v[226:227], v[206:207], v[4:5] op_sel_hi:[1,0]
	v_pk_mul_f32 v[228:229], v[206:207], v[96:97] op_sel_hi:[1,0]
	v_pk_fma_f32 v[226:227], v[208:209], v[4:5], v[226:227] op_sel:[0,1,0]
	v_pk_fma_f32 v[228:229], v[208:209], v[96:97], v[228:229] op_sel:[0,1,0]
	v_pk_fma_f32 v[226:227], v[210:211], v[6:7], v[226:227] op_sel_hi:[1,0,1]
	v_pk_fma_f32 v[228:229], v[210:211], v[98:99], v[228:229] op_sel_hi:[1,0,1]
	v_pk_fma_f32 v[226:227], v[212:213], v[6:7], v[226:227] op_sel:[0,1,0]
	v_pk_fma_f32 v[228:229], v[212:213], v[98:99], v[228:229] op_sel:[0,1,0]
	v_pk_mul_f32 v[232:233], v[58:59], v[12:13] op_sel_hi:[1,0]
	v_add_f32_dpp v230, v227, v226 row_ror:8 row_mask:0xf bank_mask:0xf
	v_pk_mul_f32 v[234:235], v[58:59], v[12:13] op_sel:[0,1]
	v_pk_mul_f32 v[236:237], v[58:59], v[14:15] op_sel_hi:[1,0]
	v_add_f32_dpp v230, v230, v230 quad_perm:[1,0,3,2] row_mask:0xf bank_mask:0xf
	v_pk_mul_f32 v[238:239], v[58:59], v[14:15] op_sel:[0,1]
	ds_read_b128 v[96:99], v240 offset:36448
	v_add_f32_dpp v230, v230, v230 quad_perm:[2,3,0,1] row_mask:0xf bank_mask:0xf
	v_pk_fma_f32 v[232:233], v[206:207], v[0:1], v[232:233] op_sel_hi:[1,0,1]
	v_pk_fma_f32 v[234:235], v[208:209], v[0:1], v[234:235] op_sel:[0,1,0]
	v_add_f32_dpp v230, v230, v230 row_half_mirror row_mask:0xf bank_mask:0xf
	v_pk_fma_f32 v[236:237], v[210:211], v[2:3], v[236:237] op_sel_hi:[1,0,1]
	v_pk_fma_f32 v[238:239], v[212:213], v[2:3], v[238:239] op_sel:[0,1,0]
	v_mov_b32_dpp v231, v230 row_ror:8 row_mask:0xf bank_mask:0xf
	ds_write_b64 v217, v[228:229] offset:2304
	v_pk_fma_f32 v[206:207], v[8:9], v[230:231], v[232:233] op_sel_hi:[0,1,1] neg_lo:[1,0,0] neg_hi:[1,0,0]
	v_pk_fma_f32 v[208:209], v[8:9], v[230:231], v[234:235] op_sel:[1,0,0] neg_lo:[1,0,0] neg_hi:[1,0,0]
	v_pk_fma_f32 v[210:211], v[10:11], v[230:231], v[236:237] op_sel_hi:[0,1,1] neg_lo:[1,0,0] neg_hi:[1,0,0]
	v_pk_fma_f32 v[212:213], v[10:11], v[230:231], v[238:239] op_sel:[1,0,0] neg_lo:[1,0,0] neg_hi:[1,0,0]
	s_waitcnt lgkmcnt(7)
	ds_read_b128 v[4:7], v240 offset:10880
	ds_read_b128 v[56:59], v242 offset:45632
	ds_read_b128 v[12:15], v240 offset:28288
	ds_read_b128 v[0:3], v240 offset:2176
	ds_read_b128 v[8:11], v240 offset:19584
	v_pk_mul_f32 v[226:227], v[206:207], v[84:85] op_sel_hi:[1,0]
	v_pk_mul_f32 v[228:229], v[206:207], v[222:223] op_sel_hi:[1,0]
	v_pk_fma_f32 v[226:227], v[208:209], v[84:85], v[226:227] op_sel:[0,1,0]
	v_pk_fma_f32 v[228:229], v[208:209], v[222:223], v[228:229] op_sel:[0,1,0]
	v_pk_fma_f32 v[226:227], v[210:211], v[86:87], v[226:227] op_sel_hi:[1,0,1]
	v_pk_fma_f32 v[228:229], v[210:211], v[224:225], v[228:229] op_sel_hi:[1,0,1]
	v_pk_fma_f32 v[226:227], v[212:213], v[86:87], v[226:227] op_sel:[0,1,0]
	v_pk_fma_f32 v[228:229], v[212:213], v[224:225], v[228:229] op_sel:[0,1,0]
	v_pk_mul_f32 v[232:233], v[60:61], v[92:93] op_sel_hi:[1,0]
	v_add_f32_dpp v230, v227, v226 row_ror:8 row_mask:0xf bank_mask:0xf
	v_pk_mul_f32 v[234:235], v[60:61], v[92:93] op_sel:[0,1]
	v_pk_mul_f32 v[236:237], v[60:61], v[94:95] op_sel_hi:[1,0]
	v_add_f32_dpp v230, v230, v230 quad_perm:[1,0,3,2] row_mask:0xf bank_mask:0xf
	v_pk_mul_f32 v[238:239], v[60:61], v[94:95] op_sel:[0,1]
	ds_read_b128 v[222:225], v240 offset:36720
	v_add_f32_dpp v230, v230, v230 quad_perm:[2,3,0,1] row_mask:0xf bank_mask:0xf
	v_pk_fma_f32 v[232:233], v[206:207], v[80:81], v[232:233] op_sel_hi:[1,0,1]
	v_pk_fma_f32 v[234:235], v[208:209], v[80:81], v[234:235] op_sel:[0,1,0]
	v_add_f32_dpp v230, v230, v230 row_half_mirror row_mask:0xf bank_mask:0xf
	v_pk_fma_f32 v[236:237], v[210:211], v[82:83], v[236:237] op_sel_hi:[1,0,1]
	v_pk_fma_f32 v[238:239], v[212:213], v[82:83], v[238:239] op_sel:[0,1,0]
	v_mov_b32_dpp v231, v230 row_ror:8 row_mask:0xf bank_mask:0xf
	ds_write_b64 v217, v[228:229] offset:2880
	v_pk_fma_f32 v[206:207], v[88:89], v[230:231], v[232:233] op_sel_hi:[0,1,1] neg_lo:[1,0,0] neg_hi:[1,0,0]
	v_pk_fma_f32 v[208:209], v[88:89], v[230:231], v[234:235] op_sel:[1,0,0] neg_lo:[1,0,0] neg_hi:[1,0,0]
	v_pk_fma_f32 v[210:211], v[90:91], v[230:231], v[236:237] op_sel_hi:[0,1,1] neg_lo:[1,0,0] neg_hi:[1,0,0]
	v_pk_fma_f32 v[212:213], v[90:91], v[230:231], v[238:239] op_sel:[1,0,0] neg_lo:[1,0,0] neg_hi:[1,0,0]
	s_waitcnt lgkmcnt(8)
	ds_read_b128 v[84:87], v240 offset:11152
	ds_read_b128 v[92:95], v240 offset:28560
	ds_read_b128 v[80:83], v240 offset:2448
	ds_read_b128 v[88:91], v240 offset:19856
	v_pk_mul_f32 v[226:227], v[206:207], v[106:107] op_sel_hi:[1,0]
	v_pk_mul_f32 v[228:229], v[206:207], v[96:97] op_sel_hi:[1,0]
	v_pk_fma_f32 v[226:227], v[208:209], v[106:107], v[226:227] op_sel:[0,1,0]
	v_pk_fma_f32 v[228:229], v[208:209], v[96:97], v[228:229] op_sel:[0,1,0]
	v_pk_fma_f32 v[226:227], v[210:211], v[108:109], v[226:227] op_sel_hi:[1,0,1]
	v_pk_fma_f32 v[228:229], v[210:211], v[98:99], v[228:229] op_sel_hi:[1,0,1]
	v_pk_fma_f32 v[226:227], v[212:213], v[108:109], v[226:227] op_sel:[0,1,0]
	v_pk_fma_f32 v[228:229], v[212:213], v[98:99], v[228:229] op_sel:[0,1,0]
	v_pk_mul_f32 v[232:233], v[62:63], v[114:115] op_sel_hi:[1,0]
	v_add_f32_dpp v230, v227, v226 row_ror:8 row_mask:0xf bank_mask:0xf
	v_pk_mul_f32 v[234:235], v[62:63], v[114:115] op_sel:[0,1]
	v_pk_mul_f32 v[236:237], v[62:63], v[116:117] op_sel_hi:[1,0]
	v_add_f32_dpp v230, v230, v230 quad_perm:[1,0,3,2] row_mask:0xf bank_mask:0xf
	v_pk_mul_f32 v[238:239], v[62:63], v[116:117] op_sel:[0,1]
	ds_read_b128 v[96:99], v240 offset:36992
	v_add_f32_dpp v230, v230, v230 quad_perm:[2,3,0,1] row_mask:0xf bank_mask:0xf
	v_pk_fma_f32 v[232:233], v[206:207], v[102:103], v[232:233] op_sel_hi:[1,0,1]
	v_pk_fma_f32 v[234:235], v[208:209], v[102:103], v[234:235] op_sel:[0,1,0]
	v_add_f32_dpp v230, v230, v230 row_half_mirror row_mask:0xf bank_mask:0xf
	v_pk_fma_f32 v[236:237], v[210:211], v[104:105], v[236:237] op_sel_hi:[1,0,1]
	v_pk_fma_f32 v[238:239], v[212:213], v[104:105], v[238:239] op_sel:[0,1,0]
	v_mov_b32_dpp v231, v230 row_ror:8 row_mask:0xf bank_mask:0xf
	ds_write_b64 v217, v[228:229] offset:3456
	v_pk_fma_f32 v[206:207], v[110:111], v[230:231], v[232:233] op_sel_hi:[0,1,1] neg_lo:[1,0,0] neg_hi:[1,0,0]
	v_pk_fma_f32 v[208:209], v[110:111], v[230:231], v[234:235] op_sel:[1,0,0] neg_lo:[1,0,0] neg_hi:[1,0,0]
	v_pk_fma_f32 v[210:211], v[112:113], v[230:231], v[236:237] op_sel_hi:[0,1,1] neg_lo:[1,0,0] neg_hi:[1,0,0]
	v_pk_fma_f32 v[212:213], v[112:113], v[230:231], v[238:239] op_sel:[1,0,0] neg_lo:[1,0,0] neg_hi:[1,0,0]
	s_waitcnt lgkmcnt(7)
; template <int CTRL> __device__ __forceinline__ float dppf(float x) { return __builtin_bit_cast(float, __builtin_amdgcn_update_dpp(0, __builtin_bit_cast(int, x), CTRL, 0xF, 0xF, false)); }
; __device__ __forceinline__ void phase_rwkv_scan(const Fr& F, int jr) {
;     ...
;                         const int p = pg + pi, pn = p < 63 ? p + 1 : 63;
;                         const f32x4 w4n = PW[pn * 16], k4n = PW[1024 + pn * 16], b4n = PW[2048 + pn * 16], d4n = PW[3072 + pn * 16], r4n = PR[pn * 16];
;                         const float vvn = PV[pn * 32];
;                         f32x2 t = S01 * k4.xy; t = S23 * k4.zw + t; float sa = t.x + t.y;
;                         sa += dppf<0x128>(sa);
;                         const f32x2 dv01 = d4.xy * vv, dv23 = d4.zw * vv;
;                         sa += dppf<0x124>(sa);
;                         const f32x2 e01 = S01 * w4.xy + dv01;
;                         sa += dppf<0x122>(sa);
;                         const f32x2 e23 = S23 * w4.zw + dv23;
;                         sa += dppf<0x121>(sa);
;                         S01 = e01 - b4.xy * sa; S23 = e23 - b4.zw * sa;
;                         f32x2 u = S01 * r4.xy; u = S23 * r4.zw + u;
;                         PY[pi * 64] = u.x + u.y;
;                         w4 = w4n; k4 = k4n; b4 = b4n; d4 = d4n; r4 = r4n; vv = vvn;
	ds_read_b128 v[106:109], v240 offset:11424
	ds_read_b128 v[60:63], v242 offset:46160
	ds_read_b128 v[114:117], v240 offset:28832
	ds_read_b128 v[102:105], v240 offset:2720
	ds_read_b128 v[110:113], v240 offset:20128
	v_pk_mul_f32 v[226:227], v[206:207], v[4:5] op_sel_hi:[1,0]
	v_pk_mul_f32 v[228:229], v[206:207], v[222:223] op_sel_hi:[1,0]
	v_pk_fma_f32 v[226:227], v[208:209], v[4:5], v[226:227] op_sel:[0,1,0]
	v_pk_fma_f32 v[228:229], v[208:209], v[222:223], v[228:229] op_sel:[0,1,0]
	v_pk_fma_f32 v[226:227], v[210:211], v[6:7], v[226:227] op_sel_hi:[1,0,1]
	v_pk_fma_f32 v[228:229], v[210:211], v[224:225], v[228:229] op_sel_hi:[1,0,1]
	v_pk_fma_f32 v[226:227], v[212:213], v[6:7], v[226:227] op_sel:[0,1,0]
	v_pk_fma_f32 v[228:229], v[212:213], v[224:225], v[228:229] op_sel:[0,1,0]
	v_pk_mul_f32 v[232:233], v[56:57], v[12:13] op_sel_hi:[1,0]
	v_add_f32_dpp v230, v227, v226 row_ror:8 row_mask:0xf bank_mask:0xf
	v_pk_mul_f32 v[234:235], v[56:57], v[12:13] op_sel:[0,1]
	v_pk_mul_f32 v[236:237], v[56:57], v[14:15] op_sel_hi:[1,0]
	v_add_f32_dpp v230, v230, v230 quad_perm:[1,0,3,2] row_mask:0xf bank_mask:0xf
	v_pk_mul_f32 v[238:239], v[56:57], v[14:15] op_sel:[0,1]
	ds_read_b128 v[222:225], v240 offset:37264
	v_add_f32_dpp v230, v230, v230 quad_perm:[2,3,0,1] row_mask:0xf bank_mask:0xf
	v_pk_fma_f32 v[232:233], v[206:207], v[0:1], v[232:233] op_sel_hi:[1,0,1]
	v_pk_fma_f32 v[234:235], v[208:209], v[0:1], v[234:235] op_sel:[0,1,0]
	v_add_f32_dpp v230, v230, v230 row_half_mirror row_mask:0xf bank_mask:0xf
	v_pk_fma_f32 v[236:237], v[210:211], v[2:3], v[236:237] op_sel_hi:[1,0,1]
	v_pk_fma_f32 v[238:239], v[212:213], v[2:3], v[238:239] op_sel:[0,1,0]
	v_mov_b32_dpp v231, v230 row_ror:8 row_mask:0xf bank_mask:0xf
	ds_write_b64 v217, v[228:229] offset:4032
	v_pk_fma_f32 v[206:207], v[8:9], v[230:231], v[232:233] op_sel_hi:[0,1,1] neg_lo:[1,0,0] neg_hi:[1,0,0]
	v_pk_fma_f32 v[208:209], v[8:9], v[230:231], v[234:235] op_sel:[1,0,0] neg_lo:[1,0,0] neg_hi:[1,0,0]
	v_pk_fma_f32 v[210:211], v[10:11], v[230:231], v[236:237] op_sel_hi:[0,1,1] neg_lo:[1,0,0] neg_hi:[1,0,0]
	v_pk_fma_f32 v[212:213], v[10:11], v[230:231], v[238:239] op_sel:[1,0,0] neg_lo:[1,0,0] neg_hi:[1,0,0]
	s_waitcnt lgkmcnt(8)
	ds_read_b128 v[4:7], v240 offset:11696
	ds_read_b128 v[12:15], v240 offset:29104
	ds_read_b128 v[0:3], v240 offset:2992
	ds_read_b128 v[8:11], v240 offset:20400
	v_pk_mul_f32 v[226:227], v[206:207], v[84:85] op_sel_hi:[1,0]
	v_pk_mul_f32 v[228:229], v[206:207], v[96:97] op_sel_hi:[1,0]
	v_pk_fma_f32 v[226:227], v[208:209], v[84:85], v[226:227] op_sel:[0,1,0]
	v_pk_fma_f32 v[228:229], v[208:209], v[96:97], v[228:229] op_sel:[0,1,0]
	v_pk_fma_f32 v[226:227], v[210:211], v[86:87], v[226:227] op_sel_hi:[1,0,1]
	v_pk_fma_f32 v[228:229], v[210:211], v[98:99], v[228:229] op_sel_hi:[1,0,1]
	v_pk_fma_f32 v[226:227], v[212:213], v[86:87], v[226:227] op_sel:[0,1,0]
	v_pk_fma_f32 v[228:229], v[212:213], v[98:99], v[228:229] op_sel:[0,1,0]
	v_pk_mul_f32 v[232:233], v[58:59], v[92:93] op_sel_hi:[1,0]
	v_add_f32_dpp v230, v227, v226 row_ror:8 row_mask:0xf bank_mask:0xf
	v_pk_mul_f32 v[234:235], v[58:59], v[92:93] op_sel:[0,1]
	v_pk_mul_f32 v[236:237], v[58:59], v[94:95] op_sel_hi:[1,0]
	v_add_f32_dpp v230, v230, v230 quad_perm:[1,0,3,2] row_mask:0xf bank_mask:0xf
	v_pk_mul_f32 v[238:239], v[58:59], v[94:95] op_sel:[0,1]
	ds_read_b128 v[96:99], v240 offset:37536
	v_add_f32_dpp v230, v230, v230 quad_perm:[2,3,0,1] row_mask:0xf bank_mask:0xf
	v_pk_fma_f32 v[232:233], v[206:207], v[80:81], v[232:233] op_sel_hi:[1,0,1]
	v_pk_fma_f32 v[234:235], v[208:209], v[80:81], v[234:235] op_sel:[0,1,0]
	v_add_f32_dpp v230, v230, v230 row_half_mirror row_mask:0xf bank_mask:0xf
	v_pk_fma_f32 v[236:237], v[210:211], v[82:83], v[236:237] op_sel_hi:[1,0,1]
	v_pk_fma_f32 v[238:239], v[212:213], v[82:83], v[238:239] op_sel:[0,1,0]
	v_mov_b32_dpp v231, v230 row_ror:8 row_mask:0xf bank_mask:0xf
	ds_write_b64 v217, v[228:229] offset:4608
	v_pk_fma_f32 v[206:207], v[88:89], v[230:231], v[232:233] op_sel_hi:[0,1,1] neg_lo:[1,0,0] neg_hi:[1,0,0]
	v_pk_fma_f32 v[208:209], v[88:89], v[230:231], v[234:235] op_sel:[1,0,0] neg_lo:[1,0,0] neg_hi:[1,0,0]
	v_pk_fma_f32 v[210:211], v[90:91], v[230:231], v[236:237] op_sel_hi:[0,1,1] neg_lo:[1,0,0] neg_hi:[1,0,0]
	v_pk_fma_f32 v[212:213], v[90:91], v[230:231], v[238:239] op_sel:[1,0,0] neg_lo:[1,0,0] neg_hi:[1,0,0]
	s_waitcnt lgkmcnt(7)
	ds_read_b128 v[84:87], v240 offset:11968
	ds_read_b128 v[56:59], v242 offset:46688
	ds_read_b128 v[92:95], v240 offset:29376
	ds_read_b128 v[80:83], v240 offset:3264
	ds_read_b128 v[88:91], v240 offset:20672
	v_pk_mul_f32 v[226:227], v[206:207], v[106:107] op_sel_hi:[1,0]
	v_pk_mul_f32 v[228:229], v[206:207], v[222:223] op_sel_hi:[1,0]
	v_pk_fma_f32 v[226:227], v[208:209], v[106:107], v[226:227] op_sel:[0,1,0]
	v_pk_fma_f32 v[228:229], v[208:209], v[222:223], v[228:229] op_sel:[0,1,0]
	v_pk_fma_f32 v[226:227], v[210:211], v[108:109], v[226:227] op_sel_hi:[1,0,1]
	v_pk_fma_f32 v[228:229], v[210:211], v[224:225], v[228:229] op_sel_hi:[1,0,1]
	v_pk_fma_f32 v[226:227], v[212:213], v[108:109], v[226:227] op_sel:[0,1,0]
	v_pk_fma_f32 v[228:229], v[212:213], v[224:225], v[228:229] op_sel:[0,1,0]
	v_pk_mul_f32 v[232:233], v[60:61], v[114:115] op_sel_hi:[1,0]
	v_add_f32_dpp v230, v227, v226 row_ror:8 row_mask:0xf bank_mask:0xf
	v_pk_mul_f32 v[234:235], v[60:61], v[114:115] op_sel:[0,1]
	v_pk_mul_f32 v[236:237], v[60:61], v[116:117] op_sel_hi:[1,0]
	v_add_f32_dpp v230, v230, v230 quad_perm:[1,0,3,2] row_mask:0xf bank_mask:0xf
	v_pk_mul_f32 v[238:239], v[60:61], v[116:117] op_sel:[0,1]
	ds_read_b128 v[222:225], v240 offset:37808
	v_add_f32_dpp v230, v230, v230 quad_perm:[2,3,0,1] row_mask:0xf bank_mask:0xf
	v_pk_fma_f32 v[232:233], v[206:207], v[102:103], v[232:233] op_sel_hi:[1,0,1]
	v_pk_fma_f32 v[234:235], v[208:209], v[102:103], v[234:235] op_sel:[0,1,0]
	v_add_f32_dpp v230, v230, v230 row_half_mirror row_mask:0xf bank_mask:0xf
	v_pk_fma_f32 v[236:237], v[210:211], v[104:105], v[236:237] op_sel_hi:[1,0,1]
	v_pk_fma_f32 v[238:239], v[212:213], v[104:105], v[238:239] op_sel:[0,1,0]
	v_mov_b32_dpp v231, v230 row_ror:8 row_mask:0xf bank_mask:0xf
	ds_write_b64 v217, v[228:229] offset:5184
	v_pk_fma_f32 v[206:207], v[110:111], v[230:231], v[232:233] op_sel_hi:[0,1,1] neg_lo:[1,0,0] neg_hi:[1,0,0]
	v_pk_fma_f32 v[208:209], v[110:111], v[230:231], v[234:235] op_sel:[1,0,0] neg_lo:[1,0,0] neg_hi:[1,0,0]
	v_pk_fma_f32 v[210:211], v[112:113], v[230:231], v[236:237] op_sel_hi:[0,1,1] neg_lo:[1,0,0] neg_hi:[1,0,0]
	v_pk_fma_f32 v[212:213], v[112:113], v[230:231], v[238:239] op_sel:[1,0,0] neg_lo:[1,0,0] neg_hi:[1,0,0]
	s_waitcnt lgkmcnt(8)
; template <int CTRL> __device__ __forceinline__ float dppf(float x) { return __builtin_bit_cast(float, __builtin_amdgcn_update_dpp(0, __builtin_bit_cast(int, x), CTRL, 0xF, 0xF, false)); }
; __device__ __forceinline__ void phase_rwkv_scan(const Fr& F, int jr) {
;     ...
;                         const int p = pg + pi, pn = p < 63 ? p + 1 : 63;
;                         const f32x4 w4n = PW[pn * 16], k4n = PW[1024 + pn * 16], b4n = PW[2048 + pn * 16], d4n = PW[3072 + pn * 16], r4n = PR[pn * 16];
;                         const float vvn = PV[pn * 32];
;                         f32x2 t = S01 * k4.xy; t = S23 * k4.zw + t; float sa = t.x + t.y;
;                         sa += dppf<0x128>(sa);
;                         const f32x2 dv01 = d4.xy * vv, dv23 = d4.zw * vv;
;                         sa += dppf<0x124>(sa);
;                         const f32x2 e01 = S01 * w4.xy + dv01;
;                         sa += dppf<0x122>(sa);
;                         const f32x2 e23 = S23 * w4.zw + dv23;
;                         sa += dppf<0x121>(sa);
;                         S01 = e01 - b4.xy * sa; S23 = e23 - b4.zw * sa;
;                         f32x2 u = S01 * r4.xy; u = S23 * r4.zw + u;
;                         PY[pi * 64] = u.x + u.y;
;                         w4 = w4n; k4 = k4n; b4 = b4n; d4 = d4n; r4 = r4n; vv = vvn;
	ds_read_b128 v[106:109], v240 offset:12240
	ds_read_b128 v[114:117], v240 offset:29648
	ds_read_b128 v[102:105], v240 offset:3536
	ds_read_b128 v[110:113], v240 offset:20944
	v_pk_mul_f32 v[226:227], v[206:207], v[4:5] op_sel_hi:[1,0]
	v_pk_mul_f32 v[228:229], v[206:207], v[96:97] op_sel_hi:[1,0]
	v_pk_fma_f32 v[226:227], v[208:209], v[4:5], v[226:227] op_sel:[0,1,0]
	v_pk_fma_f32 v[228:229], v[208:209], v[96:97], v[228:229] op_sel:[0,1,0]
	v_pk_fma_f32 v[226:227], v[210:211], v[6:7], v[226:227] op_sel_hi:[1,0,1]
	v_pk_fma_f32 v[228:229], v[210:211], v[98:99], v[228:229] op_sel_hi:[1,0,1]
	v_pk_fma_f32 v[226:227], v[212:213], v[6:7], v[226:227] op_sel:[0,1,0]
	v_pk_fma_f32 v[228:229], v[212:213], v[98:99], v[228:229] op_sel:[0,1,0]
	v_pk_mul_f32 v[232:233], v[62:63], v[12:13] op_sel_hi:[1,0]
	v_add_f32_dpp v230, v227, v226 row_ror:8 row_mask:0xf bank_mask:0xf
	v_pk_mul_f32 v[234:235], v[62:63], v[12:13] op_sel:[0,1]
	v_pk_mul_f32 v[236:237], v[62:63], v[14:15] op_sel_hi:[1,0]
	v_add_f32_dpp v230, v230, v230 quad_perm:[1,0,3,2] row_mask:0xf bank_mask:0xf
	v_pk_mul_f32 v[238:239], v[62:63], v[14:15] op_sel:[0,1]
	ds_read_b128 v[96:99], v240 offset:38080
	v_add_f32_dpp v230, v230, v230 quad_perm:[2,3,0,1] row_mask:0xf bank_mask:0xf
	v_pk_fma_f32 v[232:233], v[206:207], v[0:1], v[232:233] op_sel_hi:[1,0,1]
	v_pk_fma_f32 v[234:235], v[208:209], v[0:1], v[234:235] op_sel:[0,1,0]
	v_add_f32_dpp v230, v230, v230 row_half_mirror row_mask:0xf bank_mask:0xf
	v_pk_fma_f32 v[236:237], v[210:211], v[2:3], v[236:237] op_sel_hi:[1,0,1]
	v_pk_fma_f32 v[238:239], v[212:213], v[2:3], v[238:239] op_sel:[0,1,0]
	v_mov_b32_dpp v231, v230 row_ror:8 row_mask:0xf bank_mask:0xf
	ds_write_b64 v217, v[228:229] offset:5760
	v_pk_fma_f32 v[206:207], v[8:9], v[230:231], v[232:233] op_sel_hi:[0,1,1] neg_lo:[1,0,0] neg_hi:[1,0,0]
	v_pk_fma_f32 v[208:209], v[8:9], v[230:231], v[234:235] op_sel:[1,0,0] neg_lo:[1,0,0] neg_hi:[1,0,0]
	v_pk_fma_f32 v[210:211], v[10:11], v[230:231], v[236:237] op_sel_hi:[0,1,1] neg_lo:[1,0,0] neg_hi:[1,0,0]
	v_pk_fma_f32 v[212:213], v[10:11], v[230:231], v[238:239] op_sel:[1,0,0] neg_lo:[1,0,0] neg_hi:[1,0,0]
	s_waitcnt lgkmcnt(7)
	ds_read_b128 v[4:7], v240 offset:12512
	ds_read_b128 v[60:63], v242 offset:47216
	ds_read_b128 v[12:15], v240 offset:29920
	ds_read_b128 v[0:3], v240 offset:3808
	ds_read_b128 v[8:11], v240 offset:21216
	v_pk_mul_f32 v[226:227], v[206:207], v[84:85] op_sel_hi:[1,0]
	v_pk_mul_f32 v[228:229], v[206:207], v[222:223] op_sel_hi:[1,0]
	v_pk_fma_f32 v[226:227], v[208:209], v[84:85], v[226:227] op_sel:[0,1,0]
	v_pk_fma_f32 v[228:229], v[208:209], v[222:223], v[228:229] op_sel:[0,1,0]
	v_pk_fma_f32 v[226:227], v[210:211], v[86:87], v[226:227] op_sel_hi:[1,0,1]
	v_pk_fma_f32 v[228:229], v[210:211], v[224:225], v[228:229] op_sel_hi:[1,0,1]
	v_pk_fma_f32 v[226:227], v[212:213], v[86:87], v[226:227] op_sel:[0,1,0]
	v_pk_fma_f32 v[228:229], v[212:213], v[224:225], v[228:229] op_sel:[0,1,0]
	v_pk_mul_f32 v[232:233], v[56:57], v[92:93] op_sel_hi:[1,0]
	v_add_f32_dpp v230, v227, v226 row_ror:8 row_mask:0xf bank_mask:0xf
	v_pk_mul_f32 v[234:235], v[56:57], v[92:93] op_sel:[0,1]
	v_pk_mul_f32 v[236:237], v[56:57], v[94:95] op_sel_hi:[1,0]
	v_add_f32_dpp v230, v230, v230 quad_perm:[1,0,3,2] row_mask:0xf bank_mask:0xf
	v_pk_mul_f32 v[238:239], v[56:57], v[94:95] op_sel:[0,1]
	ds_read_b128 v[222:225], v240 offset:38352
	v_add_f32_dpp v230, v230, v230 quad_perm:[2,3,0,1] row_mask:0xf bank_mask:0xf
	v_pk_fma_f32 v[232:233], v[206:207], v[80:81], v[232:233] op_sel_hi:[1,0,1]
	v_pk_fma_f32 v[234:235], v[208:209], v[80:81], v[234:235] op_sel:[0,1,0]
	v_add_f32_dpp v230, v230, v230 row_half_mirror row_mask:0xf bank_mask:0xf
	v_pk_fma_f32 v[236:237], v[210:211], v[82:83], v[236:237] op_sel_hi:[1,0,1]
	v_pk_fma_f32 v[238:239], v[212:213], v[82:83], v[238:239] op_sel:[0,1,0]
	v_mov_b32_dpp v231, v230 row_ror:8 row_mask:0xf bank_mask:0xf
	ds_write_b64 v217, v[228:229] offset:6336
	v_pk_fma_f32 v[206:207], v[88:89], v[230:231], v[232:233] op_sel_hi:[0,1,1] neg_lo:[1,0,0] neg_hi:[1,0,0]
	v_pk_fma_f32 v[208:209], v[88:89], v[230:231], v[234:235] op_sel:[1,0,0] neg_lo:[1,0,0] neg_hi:[1,0,0]
	v_pk_fma_f32 v[210:211], v[90:91], v[230:231], v[236:237] op_sel_hi:[0,1,1] neg_lo:[1,0,0] neg_hi:[1,0,0]
	v_pk_fma_f32 v[212:213], v[90:91], v[230:231], v[238:239] op_sel:[1,0,0] neg_lo:[1,0,0] neg_hi:[1,0,0]
	s_waitcnt lgkmcnt(8)
	ds_read_b128 v[84:87], v240 offset:12784
	ds_read_b128 v[92:95], v240 offset:30192
	ds_read_b128 v[80:83], v240 offset:4080
	ds_read_b128 v[88:91], v240 offset:21488
	v_pk_mul_f32 v[226:227], v[206:207], v[106:107] op_sel_hi:[1,0]
	v_pk_mul_f32 v[228:229], v[206:207], v[96:97] op_sel_hi:[1,0]
	v_pk_fma_f32 v[226:227], v[208:209], v[106:107], v[226:227] op_sel:[0,1,0]
	v_pk_fma_f32 v[228:229], v[208:209], v[96:97], v[228:229] op_sel:[0,1,0]
	v_pk_fma_f32 v[226:227], v[210:211], v[108:109], v[226:227] op_sel_hi:[1,0,1]
	v_pk_fma_f32 v[228:229], v[210:211], v[98:99], v[228:229] op_sel_hi:[1,0,1]
	v_pk_fma_f32 v[226:227], v[212:213], v[108:109], v[226:227] op_sel:[0,1,0]
	v_pk_fma_f32 v[228:229], v[212:213], v[98:99], v[228:229] op_sel:[0,1,0]
	v_pk_mul_f32 v[232:233], v[58:59], v[114:115] op_sel_hi:[1,0]
	v_add_f32_dpp v230, v227, v226 row_ror:8 row_mask:0xf bank_mask:0xf
	v_pk_mul_f32 v[234:235], v[58:59], v[114:115] op_sel:[0,1]
	v_pk_mul_f32 v[236:237], v[58:59], v[116:117] op_sel_hi:[1,0]
	v_add_f32_dpp v230, v230, v230 quad_perm:[1,0,3,2] row_mask:0xf bank_mask:0xf
	v_pk_mul_f32 v[238:239], v[58:59], v[116:117] op_sel:[0,1]
	ds_read_b128 v[96:99], v240 offset:38624
	v_add_f32_dpp v230, v230, v230 quad_perm:[2,3,0,1] row_mask:0xf bank_mask:0xf
	v_pk_fma_f32 v[232:233], v[206:207], v[102:103], v[232:233] op_sel_hi:[1,0,1]
	v_pk_fma_f32 v[234:235], v[208:209], v[102:103], v[234:235] op_sel:[0,1,0]
	v_add_f32_dpp v230, v230, v230 row_half_mirror row_mask:0xf bank_mask:0xf
	v_pk_fma_f32 v[236:237], v[210:211], v[104:105], v[236:237] op_sel_hi:[1,0,1]
	v_pk_fma_f32 v[238:239], v[212:213], v[104:105], v[238:239] op_sel:[0,1,0]
	v_mov_b32_dpp v231, v230 row_ror:8 row_mask:0xf bank_mask:0xf
	ds_write_b64 v217, v[228:229] offset:6912
	v_pk_fma_f32 v[206:207], v[110:111], v[230:231], v[232:233] op_sel_hi:[0,1,1] neg_lo:[1,0,0] neg_hi:[1,0,0]
	v_pk_fma_f32 v[208:209], v[110:111], v[230:231], v[234:235] op_sel:[1,0,0] neg_lo:[1,0,0] neg_hi:[1,0,0]
	v_pk_fma_f32 v[210:211], v[112:113], v[230:231], v[236:237] op_sel_hi:[0,1,1] neg_lo:[1,0,0] neg_hi:[1,0,0]
	v_pk_fma_f32 v[212:213], v[112:113], v[230:231], v[238:239] op_sel:[1,0,0] neg_lo:[1,0,0] neg_hi:[1,0,0]
	s_waitcnt lgkmcnt(7)
; __device__ __forceinline__ unsigned f2bf(float f) { unsigned u = __builtin_bit_cast(unsigned, f); return (u + 0x7fffu + ((u >> 16) & 1u)) >> 16; }
; template <int CTRL> __device__ __forceinline__ float dppf(float x) { return __builtin_bit_cast(float, __builtin_amdgcn_update_dpp(0, __builtin_bit_cast(int, x), CTRL, 0xF, 0xF, false)); }
; __device__ __forceinline__ void phase_rwkv_scan(const Fr& F, int jr) {
;     ...
;                         const int p = pg + pi, pn = p < 63 ? p + 1 : 63;
;                         const f32x4 w4n = PW[pn * 16], k4n = PW[1024 + pn * 16], b4n = PW[2048 + pn * 16], d4n = PW[3072 + pn * 16], r4n = PR[pn * 16];
;                         const float vvn = PV[pn * 32];
;                         f32x2 t = S01 * k4.xy; t = S23 * k4.zw + t; float sa = t.x + t.y;
;                         sa += dppf<0x128>(sa);
;                         const f32x2 dv01 = d4.xy * vv, dv23 = d4.zw * vv;
;                         sa += dppf<0x124>(sa);
;                         const f32x2 e01 = S01 * w4.xy + dv01;
;                         sa += dppf<0x122>(sa);
;                         const f32x2 e23 = S23 * w4.zw + dv23;
;                         sa += dppf<0x121>(sa);
;                         S01 = e01 - b4.xy * sa; S23 = e23 - b4.zw * sa;
;                         f32x2 u = S01 * r4.xy; u = S23 * r4.zw + u;
;                         PY[pi * 64] = u.x + u.y;
;                         w4 = w4n; k4 = k4n; b4 = b4n; d4 = d4n; r4 = r4n; vv = vvn;
;                     }
;                     asm volatile("s_waitcnt lgkmcnt(0)" ::: "memory");
;                     {
;                         const int j = lane >> 2, q = lane & 3; const float* yp = Ypw + j * 64 + q * 16;
;                         const f32x4 a0 = *(const f32x4*)yp, a1 = *(const f32x4*)(yp + 4), a2 = *(const f32x4*)(yp + 8), a3 = *(const f32x4*)(yp + 12);
;                         const f32x4 ssum = (a0 + a1) + (a2 + a3); const float yv = (ssum.x + ssum.y) + (ssum.z + ssum.w);
;                         const size_t row = (size_t)b * TB + tokof(s, chunk * 64 + pg + j);
;                         Yb[row * D + h * 64 + 32 * half + 4 * wave + q] = (bf16)f2bf(yv);
;                     }
	ds_read_b128 v[106:109], v240 offset:13056
	ds_read_b128 v[56:59], v242 offset:47744
	ds_read_b128 v[114:117], v240 offset:30464
	ds_read_b128 v[102:105], v240 offset:4352
	ds_read_b128 v[110:113], v240 offset:21760
	v_pk_mul_f32 v[226:227], v[206:207], v[4:5] op_sel_hi:[1,0]
	v_pk_mul_f32 v[228:229], v[206:207], v[222:223] op_sel_hi:[1,0]
	v_pk_fma_f32 v[226:227], v[208:209], v[4:5], v[226:227] op_sel:[0,1,0]
	v_pk_fma_f32 v[228:229], v[208:209], v[222:223], v[228:229] op_sel:[0,1,0]
	v_pk_fma_f32 v[226:227], v[210:211], v[6:7], v[226:227] op_sel_hi:[1,0,1]
	v_pk_fma_f32 v[228:229], v[210:211], v[224:225], v[228:229] op_sel_hi:[1,0,1]
	v_pk_fma_f32 v[226:227], v[212:213], v[6:7], v[226:227] op_sel:[0,1,0]
	v_pk_fma_f32 v[228:229], v[212:213], v[224:225], v[228:229] op_sel:[0,1,0]
	v_pk_mul_f32 v[232:233], v[60:61], v[12:13] op_sel_hi:[1,0]
	v_add_f32_dpp v230, v227, v226 row_ror:8 row_mask:0xf bank_mask:0xf
	v_pk_mul_f32 v[234:235], v[60:61], v[12:13] op_sel:[0,1]
	v_pk_mul_f32 v[236:237], v[60:61], v[14:15] op_sel_hi:[1,0]
	v_add_f32_dpp v230, v230, v230 quad_perm:[1,0,3,2] row_mask:0xf bank_mask:0xf
	v_pk_mul_f32 v[238:239], v[60:61], v[14:15] op_sel:[0,1]
	ds_read_b128 v[222:225], v240 offset:38896
	v_add_f32_dpp v230, v230, v230 quad_perm:[2,3,0,1] row_mask:0xf bank_mask:0xf
	v_pk_fma_f32 v[232:233], v[206:207], v[0:1], v[232:233] op_sel_hi:[1,0,1]
	v_pk_fma_f32 v[234:235], v[208:209], v[0:1], v[234:235] op_sel:[0,1,0]
	v_add_f32_dpp v230, v230, v230 row_half_mirror row_mask:0xf bank_mask:0xf
	v_pk_fma_f32 v[236:237], v[210:211], v[2:3], v[236:237] op_sel_hi:[1,0,1]
	v_pk_fma_f32 v[238:239], v[212:213], v[2:3], v[238:239] op_sel:[0,1,0]
	v_mov_b32_dpp v231, v230 row_ror:8 row_mask:0xf bank_mask:0xf
	ds_write_b64 v217, v[228:229] offset:7488
	v_pk_fma_f32 v[206:207], v[8:9], v[230:231], v[232:233] op_sel_hi:[0,1,1] neg_lo:[1,0,0] neg_hi:[1,0,0]
	v_pk_fma_f32 v[208:209], v[8:9], v[230:231], v[234:235] op_sel:[1,0,0] neg_lo:[1,0,0] neg_hi:[1,0,0]
	v_pk_fma_f32 v[210:211], v[10:11], v[230:231], v[236:237] op_sel_hi:[0,1,1] neg_lo:[1,0,0] neg_hi:[1,0,0]
	v_pk_fma_f32 v[212:213], v[10:11], v[230:231], v[238:239] op_sel:[1,0,0] neg_lo:[1,0,0] neg_hi:[1,0,0]
	s_waitcnt lgkmcnt(8)
	ds_read_b128 v[4:7], v240 offset:13328
	ds_read_b128 v[12:15], v240 offset:30736
	ds_read_b128 v[0:3], v240 offset:4624
	ds_read_b128 v[8:11], v240 offset:22032
	v_pk_mul_f32 v[226:227], v[206:207], v[84:85] op_sel_hi:[1,0]
	v_pk_mul_f32 v[228:229], v[206:207], v[96:97] op_sel_hi:[1,0]
	v_pk_fma_f32 v[226:227], v[208:209], v[84:85], v[226:227] op_sel:[0,1,0]
	v_pk_fma_f32 v[228:229], v[208:209], v[96:97], v[228:229] op_sel:[0,1,0]
	v_pk_fma_f32 v[226:227], v[210:211], v[86:87], v[226:227] op_sel_hi:[1,0,1]
	v_pk_fma_f32 v[228:229], v[210:211], v[98:99], v[228:229] op_sel_hi:[1,0,1]
	v_pk_fma_f32 v[226:227], v[212:213], v[86:87], v[226:227] op_sel:[0,1,0]
	v_pk_fma_f32 v[228:229], v[212:213], v[98:99], v[228:229] op_sel:[0,1,0]
	v_pk_mul_f32 v[232:233], v[62:63], v[92:93] op_sel_hi:[1,0]
	v_add_f32_dpp v230, v227, v226 row_ror:8 row_mask:0xf bank_mask:0xf
	v_pk_mul_f32 v[234:235], v[62:63], v[92:93] op_sel:[0,1]
	v_pk_mul_f32 v[236:237], v[62:63], v[94:95] op_sel_hi:[1,0]
	v_add_f32_dpp v230, v230, v230 quad_perm:[1,0,3,2] row_mask:0xf bank_mask:0xf
	v_pk_mul_f32 v[238:239], v[62:63], v[94:95] op_sel:[0,1]
	ds_read_b128 v[96:99], v240 offset:39168
	v_add_f32_dpp v230, v230, v230 quad_perm:[2,3,0,1] row_mask:0xf bank_mask:0xf
	v_pk_fma_f32 v[232:233], v[206:207], v[80:81], v[232:233] op_sel_hi:[1,0,1]
	v_pk_fma_f32 v[234:235], v[208:209], v[80:81], v[234:235] op_sel:[0,1,0]
	v_add_f32_dpp v230, v230, v230 row_half_mirror row_mask:0xf bank_mask:0xf
	v_pk_fma_f32 v[236:237], v[210:211], v[82:83], v[236:237] op_sel_hi:[1,0,1]
	v_pk_fma_f32 v[238:239], v[212:213], v[82:83], v[238:239] op_sel:[0,1,0]
	v_mov_b32_dpp v231, v230 row_ror:8 row_mask:0xf bank_mask:0xf
	ds_write_b64 v217, v[228:229] offset:8064
	v_pk_fma_f32 v[206:207], v[88:89], v[230:231], v[232:233] op_sel_hi:[0,1,1] neg_lo:[1,0,0] neg_hi:[1,0,0]
	v_pk_fma_f32 v[208:209], v[88:89], v[230:231], v[234:235] op_sel:[1,0,0] neg_lo:[1,0,0] neg_hi:[1,0,0]
	v_pk_fma_f32 v[210:211], v[90:91], v[230:231], v[236:237] op_sel_hi:[0,1,1] neg_lo:[1,0,0] neg_hi:[1,0,0]
	v_pk_fma_f32 v[212:213], v[90:91], v[230:231], v[238:239] op_sel:[1,0,0] neg_lo:[1,0,0] neg_hi:[1,0,0]
	s_waitcnt lgkmcnt(7)
	v_pk_mul_f32 v[228:229], v[206:207], v[222:223] op_sel_hi:[1,0]
	v_add_u32_e32 v243, s15, v219
	v_pk_fma_f32 v[228:229], v[208:209], v[222:223], v[228:229] op_sel:[0,1,0]
	v_lshl_add_u32 v243, v243, 11, v220
	v_pk_fma_f32 v[228:229], v[210:211], v[224:225], v[228:229] op_sel_hi:[1,0,1]
	v_pk_fma_f32 v[228:229], v[212:213], v[224:225], v[228:229] op_sel:[0,1,0]
	s_waitcnt lgkmcnt(6)
	ds_write_b64 v217, v[228:229] offset:8640
	ds_read_b128 v[24:27], v218 offset:0
	ds_read_b128 v[28:31], v218 offset:16
	ds_read_b128 v[32:35], v218 offset:32
	ds_read_b128 v[36:39], v218 offset:48
	ds_read_b128 v[40:43], v218 offset:64
	ds_read_b128 v[44:47], v218 offset:80
	ds_read_b128 v[48:51], v218 offset:96
	ds_read_b128 v[52:55], v218 offset:112
	s_waitcnt lgkmcnt(4)
	v_pk_add_f32 v[24:25], v[24:25], v[26:27]
	v_pk_add_f32 v[28:29], v[28:29], v[30:31]
	v_pk_add_f32 v[32:33], v[32:33], v[34:35]
	v_pk_add_f32 v[36:37], v[36:37], v[38:39]
	v_pk_add_f32 v[24:25], v[24:25], v[28:29]
	s_waitcnt lgkmcnt(0)
; __device__ __forceinline__ unsigned f2bf(float f) { unsigned u = __builtin_bit_cast(unsigned, f); return (u + 0x7fffu + ((u >> 16) & 1u)) >> 16; }
; template <int CTRL> __device__ __forceinline__ float dppf(float x) { return __builtin_bit_cast(float, __builtin_amdgcn_update_dpp(0, __builtin_bit_cast(int, x), CTRL, 0xF, 0xF, false)); }
; __device__ __forceinline__ void phase_rwkv_scan(const Fr& F, int jr) {
;     ...
;                         const int p = pg + pi, pn = p < 63 ? p + 1 : 63;
;                         const f32x4 w4n = PW[pn * 16], k4n = PW[1024 + pn * 16], b4n = PW[2048 + pn * 16], d4n = PW[3072 + pn * 16], r4n = PR[pn * 16];
;                         const float vvn = PV[pn * 32];
;                         f32x2 t = S01 * k4.xy; t = S23 * k4.zw + t; float sa = t.x + t.y;
;                         sa += dppf<0x128>(sa);
;                         const f32x2 dv01 = d4.xy * vv, dv23 = d4.zw * vv;
;                         sa += dppf<0x124>(sa);
;                         const f32x2 e01 = S01 * w4.xy + dv01;
;                         sa += dppf<0x122>(sa);
;                         const f32x2 e23 = S23 * w4.zw + dv23;
;                         sa += dppf<0x121>(sa);
;                         S01 = e01 - b4.xy * sa; S23 = e23 - b4.zw * sa;
;                         f32x2 u = S01 * r4.xy; u = S23 * r4.zw + u;
;                         PY[pi * 64] = u.x + u.y;
;                         w4 = w4n; k4 = k4n; b4 = b4n; d4 = d4n; r4 = r4n; vv = vvn;
;     ...
;                         const size_t row = (size_t)b * TB + tokof(s, chunk * 64 + pg + j);
;                         Yb[row * D + h * 64 + 32 * half + 4 * wave + q] = (bf16)f2bf(yv);
;                     }
	v_pk_add_f32 v[40:41], v[40:41], v[42:43]
	v_pk_add_f32 v[44:45], v[44:45], v[46:47]
	v_pk_add_f32 v[32:33], v[32:33], v[36:37]
	v_pk_add_f32 v[48:49], v[48:49], v[50:51]
	v_pk_add_f32 v[52:53], v[52:53], v[54:55]
	v_pk_add_f32 v[40:41], v[40:41], v[44:45]
	v_pk_add_f32 v[24:25], v[24:25], v[32:33]
	v_pk_add_f32 v[48:49], v[48:49], v[52:53]
	s_add_i32 s15, s15, s19
	v_pk_add_f32 v[40:41], v[40:41], v[48:49]
	v_pk_add_f32 v[24:25], v[24:25], v[40:41] op_sel:[0,1] op_sel_hi:[1,0]
	v_cvt_pk_bf16_f32 v244, v24, v25
	global_store_dword v243, v244, s[20:21]
	ds_read_b128 v[84:87], v240 offset:13600
	ds_read_b128 v[60:63], v242 offset:48272
	v_pk_mul_f32 v[226:227], v[206:207], v[106:107] op_sel_hi:[1,0]
	v_pk_mul_f32 v[232:233], v[56:57], v[114:115] op_sel_hi:[1,0]
	v_pk_fma_f32 v[226:227], v[208:209], v[106:107], v[226:227] op_sel:[0,1,0]
	v_pk_mul_f32 v[234:235], v[56:57], v[114:115] op_sel:[0,1]
	v_pk_fma_f32 v[226:227], v[210:211], v[108:109], v[226:227] op_sel_hi:[1,0,1]
	v_pk_mul_f32 v[236:237], v[56:57], v[116:117] op_sel_hi:[1,0]
	v_pk_fma_f32 v[226:227], v[212:213], v[108:109], v[226:227] op_sel:[0,1,0]
	v_pk_mul_f32 v[238:239], v[56:57], v[116:117] op_sel:[0,1]
	ds_read_b128 v[92:95], v240 offset:31008
	v_add_f32_dpp v230, v227, v226 row_ror:8 row_mask:0xf bank_mask:0xf
	v_pk_fma_f32 v[232:233], v[206:207], v[102:103], v[232:233] op_sel_hi:[1,0,1]
	v_pk_fma_f32 v[234:235], v[208:209], v[102:103], v[234:235] op_sel:[0,1,0]
	v_add_f32_dpp v230, v230, v230 quad_perm:[1,0,3,2] row_mask:0xf bank_mask:0xf
	v_pk_fma_f32 v[236:237], v[210:211], v[104:105], v[236:237] op_sel_hi:[1,0,1]
	v_pk_fma_f32 v[238:239], v[212:213], v[104:105], v[238:239] op_sel:[0,1,0]
	v_add_f32_dpp v230, v230, v230 quad_perm:[2,3,0,1] row_mask:0xf bank_mask:0xf
	ds_read_b128 v[222:225], v240 offset:39440
	ds_read_b128 v[80:83], v240 offset:4896
	v_add_f32_dpp v230, v230, v230 row_half_mirror row_mask:0xf bank_mask:0xf
	ds_read_b128 v[88:91], v240 offset:22304
	s_nop 0
	v_mov_b32_dpp v231, v230 row_ror:8 row_mask:0xf bank_mask:0xf
	v_pk_fma_f32 v[206:207], v[110:111], v[230:231], v[232:233] op_sel_hi:[0,1,1] neg_lo:[1,0,0] neg_hi:[1,0,0]
	v_pk_fma_f32 v[208:209], v[110:111], v[230:231], v[234:235] op_sel:[1,0,0] neg_lo:[1,0,0] neg_hi:[1,0,0]
	v_pk_fma_f32 v[210:211], v[112:113], v[230:231], v[236:237] op_sel_hi:[0,1,1] neg_lo:[1,0,0] neg_hi:[1,0,0]
	v_pk_fma_f32 v[212:213], v[112:113], v[230:231], v[238:239] op_sel:[1,0,0] neg_lo:[1,0,0] neg_hi:[1,0,0]
	ds_read_b128 v[106:109], v240 offset:13872
	ds_read_b128 v[114:117], v240 offset:31280
	ds_read_b128 v[102:105], v240 offset:5168
	ds_read_b128 v[110:113], v240 offset:22576
	v_pk_mul_f32 v[226:227], v[206:207], v[4:5] op_sel_hi:[1,0]
	v_pk_mul_f32 v[228:229], v[206:207], v[96:97] op_sel_hi:[1,0]
	v_pk_fma_f32 v[226:227], v[208:209], v[4:5], v[226:227] op_sel:[0,1,0]
	v_pk_fma_f32 v[228:229], v[208:209], v[96:97], v[228:229] op_sel:[0,1,0]
	v_pk_fma_f32 v[226:227], v[210:211], v[6:7], v[226:227] op_sel_hi:[1,0,1]
	v_pk_fma_f32 v[228:229], v[210:211], v[98:99], v[228:229] op_sel_hi:[1,0,1]
	v_pk_fma_f32 v[226:227], v[212:213], v[6:7], v[226:227] op_sel:[0,1,0]
	v_pk_fma_f32 v[228:229], v[212:213], v[98:99], v[228:229] op_sel:[0,1,0]
	v_pk_mul_f32 v[232:233], v[58:59], v[12:13] op_sel_hi:[1,0]
	v_add_f32_dpp v230, v227, v226 row_ror:8 row_mask:0xf bank_mask:0xf
	v_pk_mul_f32 v[234:235], v[58:59], v[12:13] op_sel:[0,1]
	v_pk_mul_f32 v[236:237], v[58:59], v[14:15] op_sel_hi:[1,0]
	v_add_f32_dpp v230, v230, v230 quad_perm:[1,0,3,2] row_mask:0xf bank_mask:0xf
	v_pk_mul_f32 v[238:239], v[58:59], v[14:15] op_sel:[0,1]
	ds_read_b128 v[96:99], v240 offset:39712
	v_add_f32_dpp v230, v230, v230 quad_perm:[2,3,0,1] row_mask:0xf bank_mask:0xf
	v_pk_fma_f32 v[232:233], v[206:207], v[0:1], v[232:233] op_sel_hi:[1,0,1]
	v_pk_fma_f32 v[234:235], v[208:209], v[0:1], v[234:235] op_sel:[0,1,0]
	v_add_f32_dpp v230, v230, v230 row_half_mirror row_mask:0xf bank_mask:0xf
	v_pk_fma_f32 v[236:237], v[210:211], v[2:3], v[236:237] op_sel_hi:[1,0,1]
	v_pk_fma_f32 v[238:239], v[212:213], v[2:3], v[238:239] op_sel:[0,1,0]
	v_mov_b32_dpp v231, v230 row_ror:8 row_mask:0xf bank_mask:0xf
	ds_write_b64 v217, v[228:229] offset:0
	v_pk_fma_f32 v[206:207], v[8:9], v[230:231], v[232:233] op_sel_hi:[0,1,1] neg_lo:[1,0,0] neg_hi:[1,0,0]
	v_pk_fma_f32 v[208:209], v[8:9], v[230:231], v[234:235] op_sel:[1,0,0] neg_lo:[1,0,0] neg_hi:[1,0,0]
	v_pk_fma_f32 v[210:211], v[10:11], v[230:231], v[236:237] op_sel_hi:[0,1,1] neg_lo:[1,0,0] neg_hi:[1,0,0]
	v_pk_fma_f32 v[212:213], v[10:11], v[230:231], v[238:239] op_sel:[1,0,0] neg_lo:[1,0,0] neg_hi:[1,0,0]
	s_waitcnt lgkmcnt(6)
; template <int CTRL> __device__ __forceinline__ float dppf(float x) { return __builtin_bit_cast(float, __builtin_amdgcn_update_dpp(0, __builtin_bit_cast(int, x), CTRL, 0xF, 0xF, false)); }
; __device__ __forceinline__ void phase_rwkv_scan(const Fr& F, int jr) {
;     ...
;                         const int p = pg + pi, pn = p < 63 ? p + 1 : 63;
;                         const f32x4 w4n = PW[pn * 16], k4n = PW[1024 + pn * 16], b4n = PW[2048 + pn * 16], d4n = PW[3072 + pn * 16], r4n = PR[pn * 16];
;                         const float vvn = PV[pn * 32];
;                         f32x2 t = S01 * k4.xy; t = S23 * k4.zw + t; float sa = t.x + t.y;
;                         sa += dppf<0x128>(sa);
;                         const f32x2 dv01 = d4.xy * vv, dv23 = d4.zw * vv;
;                         sa += dppf<0x124>(sa);
;                         const f32x2 e01 = S01 * w4.xy + dv01;
;                         sa += dppf<0x122>(sa);
;                         const f32x2 e23 = S23 * w4.zw + dv23;
;                         sa += dppf<0x121>(sa);
;                         S01 = e01 - b4.xy * sa; S23 = e23 - b4.zw * sa;
;                         f32x2 u = S01 * r4.xy; u = S23 * r4.zw + u;
;                         PY[pi * 64] = u.x + u.y;
;                         w4 = w4n; k4 = k4n; b4 = b4n; d4 = d4n; r4 = r4n; vv = vvn;
	ds_read_b128 v[4:7], v240 offset:14144
	ds_read_b128 v[56:59], v242 offset:48800
	ds_read_b128 v[12:15], v240 offset:31552
	ds_read_b128 v[0:3], v240 offset:5440
	ds_read_b128 v[8:11], v240 offset:22848
	v_pk_mul_f32 v[226:227], v[206:207], v[84:85] op_sel_hi:[1,0]
	v_pk_mul_f32 v[228:229], v[206:207], v[222:223] op_sel_hi:[1,0]
	v_pk_fma_f32 v[226:227], v[208:209], v[84:85], v[226:227] op_sel:[0,1,0]
	v_pk_fma_f32 v[228:229], v[208:209], v[222:223], v[228:229] op_sel:[0,1,0]
	v_pk_fma_f32 v[226:227], v[210:211], v[86:87], v[226:227] op_sel_hi:[1,0,1]
	v_pk_fma_f32 v[228:229], v[210:211], v[224:225], v[228:229] op_sel_hi:[1,0,1]
	v_pk_fma_f32 v[226:227], v[212:213], v[86:87], v[226:227] op_sel:[0,1,0]
	v_pk_fma_f32 v[228:229], v[212:213], v[224:225], v[228:229] op_sel:[0,1,0]
	v_pk_mul_f32 v[232:233], v[60:61], v[92:93] op_sel_hi:[1,0]
	v_add_f32_dpp v230, v227, v226 row_ror:8 row_mask:0xf bank_mask:0xf
	v_pk_mul_f32 v[234:235], v[60:61], v[92:93] op_sel:[0,1]
	v_pk_mul_f32 v[236:237], v[60:61], v[94:95] op_sel_hi:[1,0]
	v_add_f32_dpp v230, v230, v230 quad_perm:[1,0,3,2] row_mask:0xf bank_mask:0xf
	v_pk_mul_f32 v[238:239], v[60:61], v[94:95] op_sel:[0,1]
	ds_read_b128 v[222:225], v240 offset:39984
	v_add_f32_dpp v230, v230, v230 quad_perm:[2,3,0,1] row_mask:0xf bank_mask:0xf
	v_pk_fma_f32 v[232:233], v[206:207], v[80:81], v[232:233] op_sel_hi:[1,0,1]
	v_pk_fma_f32 v[234:235], v[208:209], v[80:81], v[234:235] op_sel:[0,1,0]
	v_add_f32_dpp v230, v230, v230 row_half_mirror row_mask:0xf bank_mask:0xf
	v_pk_fma_f32 v[236:237], v[210:211], v[82:83], v[236:237] op_sel_hi:[1,0,1]
	v_pk_fma_f32 v[238:239], v[212:213], v[82:83], v[238:239] op_sel:[0,1,0]
	v_mov_b32_dpp v231, v230 row_ror:8 row_mask:0xf bank_mask:0xf
	ds_write_b64 v217, v[228:229] offset:576
	v_pk_fma_f32 v[206:207], v[88:89], v[230:231], v[232:233] op_sel_hi:[0,1,1] neg_lo:[1,0,0] neg_hi:[1,0,0]
	v_pk_fma_f32 v[208:209], v[88:89], v[230:231], v[234:235] op_sel:[1,0,0] neg_lo:[1,0,0] neg_hi:[1,0,0]
	v_pk_fma_f32 v[210:211], v[90:91], v[230:231], v[236:237] op_sel_hi:[0,1,1] neg_lo:[1,0,0] neg_hi:[1,0,0]
	v_pk_fma_f32 v[212:213], v[90:91], v[230:231], v[238:239] op_sel:[1,0,0] neg_lo:[1,0,0] neg_hi:[1,0,0]
	s_waitcnt lgkmcnt(8)
	ds_read_b128 v[84:87], v240 offset:14416
	ds_read_b128 v[92:95], v240 offset:31824
	ds_read_b128 v[80:83], v240 offset:5712
	ds_read_b128 v[88:91], v240 offset:23120
	v_pk_mul_f32 v[226:227], v[206:207], v[106:107] op_sel_hi:[1,0]
	v_pk_mul_f32 v[228:229], v[206:207], v[96:97] op_sel_hi:[1,0]
	v_pk_fma_f32 v[226:227], v[208:209], v[106:107], v[226:227] op_sel:[0,1,0]
	v_pk_fma_f32 v[228:229], v[208:209], v[96:97], v[228:229] op_sel:[0,1,0]
	v_pk_fma_f32 v[226:227], v[210:211], v[108:109], v[226:227] op_sel_hi:[1,0,1]
	v_pk_fma_f32 v[228:229], v[210:211], v[98:99], v[228:229] op_sel_hi:[1,0,1]
	v_pk_fma_f32 v[226:227], v[212:213], v[108:109], v[226:227] op_sel:[0,1,0]
	v_pk_fma_f32 v[228:229], v[212:213], v[98:99], v[228:229] op_sel:[0,1,0]
	v_pk_mul_f32 v[232:233], v[62:63], v[114:115] op_sel_hi:[1,0]
	v_add_f32_dpp v230, v227, v226 row_ror:8 row_mask:0xf bank_mask:0xf
	v_pk_mul_f32 v[234:235], v[62:63], v[114:115] op_sel:[0,1]
	v_pk_mul_f32 v[236:237], v[62:63], v[116:117] op_sel_hi:[1,0]
	v_add_f32_dpp v230, v230, v230 quad_perm:[1,0,3,2] row_mask:0xf bank_mask:0xf
	v_pk_mul_f32 v[238:239], v[62:63], v[116:117] op_sel:[0,1]
	ds_read_b128 v[96:99], v240 offset:40256
	v_add_f32_dpp v230, v230, v230 quad_perm:[2,3,0,1] row_mask:0xf bank_mask:0xf
	v_pk_fma_f32 v[232:233], v[206:207], v[102:103], v[232:233] op_sel_hi:[1,0,1]
	v_pk_fma_f32 v[234:235], v[208:209], v[102:103], v[234:235] op_sel:[0,1,0]
	v_add_f32_dpp v230, v230, v230 row_half_mirror row_mask:0xf bank_mask:0xf
	v_pk_fma_f32 v[236:237], v[210:211], v[104:105], v[236:237] op_sel_hi:[1,0,1]
	v_pk_fma_f32 v[238:239], v[212:213], v[104:105], v[238:239] op_sel:[0,1,0]
	v_mov_b32_dpp v231, v230 row_ror:8 row_mask:0xf bank_mask:0xf
	ds_write_b64 v217, v[228:229] offset:1152
	v_pk_fma_f32 v[206:207], v[110:111], v[230:231], v[232:233] op_sel_hi:[0,1,1] neg_lo:[1,0,0] neg_hi:[1,0,0]
	v_pk_fma_f32 v[208:209], v[110:111], v[230:231], v[234:235] op_sel:[1,0,0] neg_lo:[1,0,0] neg_hi:[1,0,0]
	v_pk_fma_f32 v[210:211], v[112:113], v[230:231], v[236:237] op_sel_hi:[0,1,1] neg_lo:[1,0,0] neg_hi:[1,0,0]
	v_pk_fma_f32 v[212:213], v[112:113], v[230:231], v[238:239] op_sel:[1,0,0] neg_lo:[1,0,0] neg_hi:[1,0,0]
	s_waitcnt lgkmcnt(7)
	ds_read_b128 v[106:109], v240 offset:14688
	ds_read_b128 v[60:63], v242 offset:49328
	ds_read_b128 v[114:117], v240 offset:32096
	ds_read_b128 v[102:105], v240 offset:5984
	ds_read_b128 v[110:113], v240 offset:23392
	v_pk_mul_f32 v[226:227], v[206:207], v[4:5] op_sel_hi:[1,0]
	v_pk_mul_f32 v[228:229], v[206:207], v[222:223] op_sel_hi:[1,0]
	v_pk_fma_f32 v[226:227], v[208:209], v[4:5], v[226:227] op_sel:[0,1,0]
	v_pk_fma_f32 v[228:229], v[208:209], v[222:223], v[228:229] op_sel:[0,1,0]
	v_pk_fma_f32 v[226:227], v[210:211], v[6:7], v[226:227] op_sel_hi:[1,0,1]
	v_pk_fma_f32 v[228:229], v[210:211], v[224:225], v[228:229] op_sel_hi:[1,0,1]
	v_pk_fma_f32 v[226:227], v[212:213], v[6:7], v[226:227] op_sel:[0,1,0]
	v_pk_fma_f32 v[228:229], v[212:213], v[224:225], v[228:229] op_sel:[0,1,0]
	v_pk_mul_f32 v[232:233], v[56:57], v[12:13] op_sel_hi:[1,0]
	v_add_f32_dpp v230, v227, v226 row_ror:8 row_mask:0xf bank_mask:0xf
	v_pk_mul_f32 v[234:235], v[56:57], v[12:13] op_sel:[0,1]
	v_pk_mul_f32 v[236:237], v[56:57], v[14:15] op_sel_hi:[1,0]
	v_add_f32_dpp v230, v230, v230 quad_perm:[1,0,3,2] row_mask:0xf bank_mask:0xf
	v_pk_mul_f32 v[238:239], v[56:57], v[14:15] op_sel:[0,1]
	ds_read_b128 v[222:225], v240 offset:40528
	v_add_f32_dpp v230, v230, v230 quad_perm:[2,3,0,1] row_mask:0xf bank_mask:0xf
	v_pk_fma_f32 v[232:233], v[206:207], v[0:1], v[232:233] op_sel_hi:[1,0,1]
	v_pk_fma_f32 v[234:235], v[208:209], v[0:1], v[234:235] op_sel:[0,1,0]
	v_add_f32_dpp v230, v230, v230 row_half_mirror row_mask:0xf bank_mask:0xf
	v_pk_fma_f32 v[236:237], v[210:211], v[2:3], v[236:237] op_sel_hi:[1,0,1]
	v_pk_fma_f32 v[238:239], v[212:213], v[2:3], v[238:239] op_sel:[0,1,0]
	v_mov_b32_dpp v231, v230 row_ror:8 row_mask:0xf bank_mask:0xf
	ds_write_b64 v217, v[228:229] offset:1728
	v_pk_fma_f32 v[206:207], v[8:9], v[230:231], v[232:233] op_sel_hi:[0,1,1] neg_lo:[1,0,0] neg_hi:[1,0,0]
	v_pk_fma_f32 v[208:209], v[8:9], v[230:231], v[234:235] op_sel:[1,0,0] neg_lo:[1,0,0] neg_hi:[1,0,0]
	v_pk_fma_f32 v[210:211], v[10:11], v[230:231], v[236:237] op_sel_hi:[0,1,1] neg_lo:[1,0,0] neg_hi:[1,0,0]
	v_pk_fma_f32 v[212:213], v[10:11], v[230:231], v[238:239] op_sel:[1,0,0] neg_lo:[1,0,0] neg_hi:[1,0,0]
	s_waitcnt lgkmcnt(8)
; template <int CTRL> __device__ __forceinline__ float dppf(float x) { return __builtin_bit_cast(float, __builtin_amdgcn_update_dpp(0, __builtin_bit_cast(int, x), CTRL, 0xF, 0xF, false)); }
; __device__ __forceinline__ void phase_rwkv_scan(const Fr& F, int jr) {
;     ...
;                         const int p = pg + pi, pn = p < 63 ? p + 1 : 63;
;                         const f32x4 w4n = PW[pn * 16], k4n = PW[1024 + pn * 16], b4n = PW[2048 + pn * 16], d4n = PW[3072 + pn * 16], r4n = PR[pn * 16];
;                         const float vvn = PV[pn * 32];
;                         f32x2 t = S01 * k4.xy; t = S23 * k4.zw + t; float sa = t.x + t.y;
;                         sa += dppf<0x128>(sa);
;                         const f32x2 dv01 = d4.xy * vv, dv23 = d4.zw * vv;
;                         sa += dppf<0x124>(sa);
;                         const f32x2 e01 = S01 * w4.xy + dv01;
;                         sa += dppf<0x122>(sa);
;                         const f32x2 e23 = S23 * w4.zw + dv23;
;                         sa += dppf<0x121>(sa);
;                         S01 = e01 - b4.xy * sa; S23 = e23 - b4.zw * sa;
;                         f32x2 u = S01 * r4.xy; u = S23 * r4.zw + u;
;                         PY[pi * 64] = u.x + u.y;
;                         w4 = w4n; k4 = k4n; b4 = b4n; d4 = d4n; r4 = r4n; vv = vvn;
	ds_read_b128 v[4:7], v240 offset:14960
	ds_read_b128 v[12:15], v240 offset:32368
	ds_read_b128 v[0:3], v240 offset:6256
	ds_read_b128 v[8:11], v240 offset:23664
	v_pk_mul_f32 v[226:227], v[206:207], v[84:85] op_sel_hi:[1,0]
	v_pk_mul_f32 v[228:229], v[206:207], v[96:97] op_sel_hi:[1,0]
	v_pk_fma_f32 v[226:227], v[208:209], v[84:85], v[226:227] op_sel:[0,1,0]
	v_pk_fma_f32 v[228:229], v[208:209], v[96:97], v[228:229] op_sel:[0,1,0]
	v_pk_fma_f32 v[226:227], v[210:211], v[86:87], v[226:227] op_sel_hi:[1,0,1]
	v_pk_fma_f32 v[228:229], v[210:211], v[98:99], v[228:229] op_sel_hi:[1,0,1]
	v_pk_fma_f32 v[226:227], v[212:213], v[86:87], v[226:227] op_sel:[0,1,0]
	v_pk_fma_f32 v[228:229], v[212:213], v[98:99], v[228:229] op_sel:[0,1,0]
	v_pk_mul_f32 v[232:233], v[58:59], v[92:93] op_sel_hi:[1,0]
	v_add_f32_dpp v230, v227, v226 row_ror:8 row_mask:0xf bank_mask:0xf
	v_pk_mul_f32 v[234:235], v[58:59], v[92:93] op_sel:[0,1]
	v_pk_mul_f32 v[236:237], v[58:59], v[94:95] op_sel_hi:[1,0]
	v_add_f32_dpp v230, v230, v230 quad_perm:[1,0,3,2] row_mask:0xf bank_mask:0xf
	v_pk_mul_f32 v[238:239], v[58:59], v[94:95] op_sel:[0,1]
	ds_read_b128 v[96:99], v240 offset:40800
	v_add_f32_dpp v230, v230, v230 quad_perm:[2,3,0,1] row_mask:0xf bank_mask:0xf
	v_pk_fma_f32 v[232:233], v[206:207], v[80:81], v[232:233] op_sel_hi:[1,0,1]
	v_pk_fma_f32 v[234:235], v[208:209], v[80:81], v[234:235] op_sel:[0,1,0]
	v_add_f32_dpp v230, v230, v230 row_half_mirror row_mask:0xf bank_mask:0xf
	v_pk_fma_f32 v[236:237], v[210:211], v[82:83], v[236:237] op_sel_hi:[1,0,1]
	v_pk_fma_f32 v[238:239], v[212:213], v[82:83], v[238:239] op_sel:[0,1,0]
	v_mov_b32_dpp v231, v230 row_ror:8 row_mask:0xf bank_mask:0xf
	ds_write_b64 v217, v[228:229] offset:2304
	v_pk_fma_f32 v[206:207], v[88:89], v[230:231], v[232:233] op_sel_hi:[0,1,1] neg_lo:[1,0,0] neg_hi:[1,0,0]
	v_pk_fma_f32 v[208:209], v[88:89], v[230:231], v[234:235] op_sel:[1,0,0] neg_lo:[1,0,0] neg_hi:[1,0,0]
	v_pk_fma_f32 v[210:211], v[90:91], v[230:231], v[236:237] op_sel_hi:[0,1,1] neg_lo:[1,0,0] neg_hi:[1,0,0]
	v_pk_fma_f32 v[212:213], v[90:91], v[230:231], v[238:239] op_sel:[1,0,0] neg_lo:[1,0,0] neg_hi:[1,0,0]
	s_waitcnt lgkmcnt(7)
	ds_read_b128 v[84:87], v240 offset:15232
	ds_read_b128 v[56:59], v242 offset:49856
	ds_read_b128 v[92:95], v240 offset:32640
	ds_read_b128 v[80:83], v240 offset:6528
	ds_read_b128 v[88:91], v240 offset:23936
	v_pk_mul_f32 v[226:227], v[206:207], v[106:107] op_sel_hi:[1,0]
	v_pk_mul_f32 v[228:229], v[206:207], v[222:223] op_sel_hi:[1,0]
	v_pk_fma_f32 v[226:227], v[208:209], v[106:107], v[226:227] op_sel:[0,1,0]
	v_pk_fma_f32 v[228:229], v[208:209], v[222:223], v[228:229] op_sel:[0,1,0]
	v_pk_fma_f32 v[226:227], v[210:211], v[108:109], v[226:227] op_sel_hi:[1,0,1]
	v_pk_fma_f32 v[228:229], v[210:211], v[224:225], v[228:229] op_sel_hi:[1,0,1]
	v_pk_fma_f32 v[226:227], v[212:213], v[108:109], v[226:227] op_sel:[0,1,0]
	v_pk_fma_f32 v[228:229], v[212:213], v[224:225], v[228:229] op_sel:[0,1,0]
	v_pk_mul_f32 v[232:233], v[60:61], v[114:115] op_sel_hi:[1,0]
	v_add_f32_dpp v230, v227, v226 row_ror:8 row_mask:0xf bank_mask:0xf
	v_pk_mul_f32 v[234:235], v[60:61], v[114:115] op_sel:[0,1]
	v_pk_mul_f32 v[236:237], v[60:61], v[116:117] op_sel_hi:[1,0]
	v_add_f32_dpp v230, v230, v230 quad_perm:[1,0,3,2] row_mask:0xf bank_mask:0xf
	v_pk_mul_f32 v[238:239], v[60:61], v[116:117] op_sel:[0,1]
	ds_read_b128 v[222:225], v240 offset:41072
	v_add_f32_dpp v230, v230, v230 quad_perm:[2,3,0,1] row_mask:0xf bank_mask:0xf
	v_pk_fma_f32 v[232:233], v[206:207], v[102:103], v[232:233] op_sel_hi:[1,0,1]
	v_pk_fma_f32 v[234:235], v[208:209], v[102:103], v[234:235] op_sel:[0,1,0]
	v_add_f32_dpp v230, v230, v230 row_half_mirror row_mask:0xf bank_mask:0xf
	v_pk_fma_f32 v[236:237], v[210:211], v[104:105], v[236:237] op_sel_hi:[1,0,1]
	v_pk_fma_f32 v[238:239], v[212:213], v[104:105], v[238:239] op_sel:[0,1,0]
	v_mov_b32_dpp v231, v230 row_ror:8 row_mask:0xf bank_mask:0xf
	ds_write_b64 v217, v[228:229] offset:2880
	v_pk_fma_f32 v[206:207], v[110:111], v[230:231], v[232:233] op_sel_hi:[0,1,1] neg_lo:[1,0,0] neg_hi:[1,0,0]
	v_pk_fma_f32 v[208:209], v[110:111], v[230:231], v[234:235] op_sel:[1,0,0] neg_lo:[1,0,0] neg_hi:[1,0,0]
	v_pk_fma_f32 v[210:211], v[112:113], v[230:231], v[236:237] op_sel_hi:[0,1,1] neg_lo:[1,0,0] neg_hi:[1,0,0]
	v_pk_fma_f32 v[212:213], v[112:113], v[230:231], v[238:239] op_sel:[1,0,0] neg_lo:[1,0,0] neg_hi:[1,0,0]
	s_waitcnt lgkmcnt(8)
	ds_read_b128 v[106:109], v240 offset:15504
	ds_read_b128 v[114:117], v240 offset:32912
	ds_read_b128 v[102:105], v240 offset:6800
	ds_read_b128 v[110:113], v240 offset:24208
	v_pk_mul_f32 v[226:227], v[206:207], v[4:5] op_sel_hi:[1,0]
	v_pk_mul_f32 v[228:229], v[206:207], v[96:97] op_sel_hi:[1,0]
	v_pk_fma_f32 v[226:227], v[208:209], v[4:5], v[226:227] op_sel:[0,1,0]
	v_pk_fma_f32 v[228:229], v[208:209], v[96:97], v[228:229] op_sel:[0,1,0]
	v_pk_fma_f32 v[226:227], v[210:211], v[6:7], v[226:227] op_sel_hi:[1,0,1]
	v_pk_fma_f32 v[228:229], v[210:211], v[98:99], v[228:229] op_sel_hi:[1,0,1]
	v_pk_fma_f32 v[226:227], v[212:213], v[6:7], v[226:227] op_sel:[0,1,0]
	v_pk_fma_f32 v[228:229], v[212:213], v[98:99], v[228:229] op_sel:[0,1,0]
	v_pk_mul_f32 v[232:233], v[62:63], v[12:13] op_sel_hi:[1,0]
	v_add_f32_dpp v230, v227, v226 row_ror:8 row_mask:0xf bank_mask:0xf
	v_pk_mul_f32 v[234:235], v[62:63], v[12:13] op_sel:[0,1]
	v_pk_mul_f32 v[236:237], v[62:63], v[14:15] op_sel_hi:[1,0]
	v_add_f32_dpp v230, v230, v230 quad_perm:[1,0,3,2] row_mask:0xf bank_mask:0xf
	v_pk_mul_f32 v[238:239], v[62:63], v[14:15] op_sel:[0,1]
	ds_read_b128 v[96:99], v240 offset:41344
	v_add_f32_dpp v230, v230, v230 quad_perm:[2,3,0,1] row_mask:0xf bank_mask:0xf
	v_pk_fma_f32 v[232:233], v[206:207], v[0:1], v[232:233] op_sel_hi:[1,0,1]
	v_pk_fma_f32 v[234:235], v[208:209], v[0:1], v[234:235] op_sel:[0,1,0]
	v_add_f32_dpp v230, v230, v230 row_half_mirror row_mask:0xf bank_mask:0xf
	v_pk_fma_f32 v[236:237], v[210:211], v[2:3], v[236:237] op_sel_hi:[1,0,1]
	v_pk_fma_f32 v[238:239], v[212:213], v[2:3], v[238:239] op_sel:[0,1,0]
	v_mov_b32_dpp v231, v230 row_ror:8 row_mask:0xf bank_mask:0xf
	ds_write_b64 v217, v[228:229] offset:3456
	v_pk_fma_f32 v[206:207], v[8:9], v[230:231], v[232:233] op_sel_hi:[0,1,1] neg_lo:[1,0,0] neg_hi:[1,0,0]
	v_pk_fma_f32 v[208:209], v[8:9], v[230:231], v[234:235] op_sel:[1,0,0] neg_lo:[1,0,0] neg_hi:[1,0,0]
	v_pk_fma_f32 v[210:211], v[10:11], v[230:231], v[236:237] op_sel_hi:[0,1,1] neg_lo:[1,0,0] neg_hi:[1,0,0]
	v_pk_fma_f32 v[212:213], v[10:11], v[230:231], v[238:239] op_sel:[1,0,0] neg_lo:[1,0,0] neg_hi:[1,0,0]
	s_waitcnt lgkmcnt(7)
; template <int CTRL> __device__ __forceinline__ float dppf(float x) { return __builtin_bit_cast(float, __builtin_amdgcn_update_dpp(0, __builtin_bit_cast(int, x), CTRL, 0xF, 0xF, false)); }
; __device__ __forceinline__ void phase_rwkv_scan(const Fr& F, int jr) {
;     ...
;                         const int p = pg + pi, pn = p < 63 ? p + 1 : 63;
;                         const f32x4 w4n = PW[pn * 16], k4n = PW[1024 + pn * 16], b4n = PW[2048 + pn * 16], d4n = PW[3072 + pn * 16], r4n = PR[pn * 16];
;                         const float vvn = PV[pn * 32];
;                         f32x2 t = S01 * k4.xy; t = S23 * k4.zw + t; float sa = t.x + t.y;
;                         sa += dppf<0x128>(sa);
;                         const f32x2 dv01 = d4.xy * vv, dv23 = d4.zw * vv;
;                         sa += dppf<0x124>(sa);
;                         const f32x2 e01 = S01 * w4.xy + dv01;
;                         sa += dppf<0x122>(sa);
;                         const f32x2 e23 = S23 * w4.zw + dv23;
;                         sa += dppf<0x121>(sa);
;                         S01 = e01 - b4.xy * sa; S23 = e23 - b4.zw * sa;
;                         f32x2 u = S01 * r4.xy; u = S23 * r4.zw + u;
;                         PY[pi * 64] = u.x + u.y;
;                         w4 = w4n; k4 = k4n; b4 = b4n; d4 = d4n; r4 = r4n; vv = vvn;
	ds_read_b128 v[4:7], v240 offset:15776
	ds_read_b128 v[60:63], v242 offset:50384
	ds_read_b128 v[12:15], v240 offset:33184
	ds_read_b128 v[0:3], v240 offset:7072
	ds_read_b128 v[8:11], v240 offset:24480
	v_pk_mul_f32 v[226:227], v[206:207], v[84:85] op_sel_hi:[1,0]
	v_pk_mul_f32 v[228:229], v[206:207], v[222:223] op_sel_hi:[1,0]
	v_pk_fma_f32 v[226:227], v[208:209], v[84:85], v[226:227] op_sel:[0,1,0]
	v_pk_fma_f32 v[228:229], v[208:209], v[222:223], v[228:229] op_sel:[0,1,0]
	v_pk_fma_f32 v[226:227], v[210:211], v[86:87], v[226:227] op_sel_hi:[1,0,1]
	v_pk_fma_f32 v[228:229], v[210:211], v[224:225], v[228:229] op_sel_hi:[1,0,1]
	v_pk_fma_f32 v[226:227], v[212:213], v[86:87], v[226:227] op_sel:[0,1,0]
	v_pk_fma_f32 v[228:229], v[212:213], v[224:225], v[228:229] op_sel:[0,1,0]
	v_pk_mul_f32 v[232:233], v[56:57], v[92:93] op_sel_hi:[1,0]
	v_add_f32_dpp v230, v227, v226 row_ror:8 row_mask:0xf bank_mask:0xf
	v_pk_mul_f32 v[234:235], v[56:57], v[92:93] op_sel:[0,1]
	v_pk_mul_f32 v[236:237], v[56:57], v[94:95] op_sel_hi:[1,0]
	v_add_f32_dpp v230, v230, v230 quad_perm:[1,0,3,2] row_mask:0xf bank_mask:0xf
	v_pk_mul_f32 v[238:239], v[56:57], v[94:95] op_sel:[0,1]
	ds_read_b128 v[222:225], v240 offset:41616
	v_add_f32_dpp v230, v230, v230 quad_perm:[2,3,0,1] row_mask:0xf bank_mask:0xf
	v_pk_fma_f32 v[232:233], v[206:207], v[80:81], v[232:233] op_sel_hi:[1,0,1]
	v_pk_fma_f32 v[234:235], v[208:209], v[80:81], v[234:235] op_sel:[0,1,0]
	v_add_f32_dpp v230, v230, v230 row_half_mirror row_mask:0xf bank_mask:0xf
	v_pk_fma_f32 v[236:237], v[210:211], v[82:83], v[236:237] op_sel_hi:[1,0,1]
	v_pk_fma_f32 v[238:239], v[212:213], v[82:83], v[238:239] op_sel:[0,1,0]
	v_mov_b32_dpp v231, v230 row_ror:8 row_mask:0xf bank_mask:0xf
	ds_write_b64 v217, v[228:229] offset:4032
	v_pk_fma_f32 v[206:207], v[88:89], v[230:231], v[232:233] op_sel_hi:[0,1,1] neg_lo:[1,0,0] neg_hi:[1,0,0]
	v_pk_fma_f32 v[208:209], v[88:89], v[230:231], v[234:235] op_sel:[1,0,0] neg_lo:[1,0,0] neg_hi:[1,0,0]
	v_pk_fma_f32 v[210:211], v[90:91], v[230:231], v[236:237] op_sel_hi:[0,1,1] neg_lo:[1,0,0] neg_hi:[1,0,0]
	v_pk_fma_f32 v[212:213], v[90:91], v[230:231], v[238:239] op_sel:[1,0,0] neg_lo:[1,0,0] neg_hi:[1,0,0]
	s_waitcnt lgkmcnt(8)
	ds_read_b128 v[84:87], v240 offset:16048
	ds_read_b128 v[92:95], v240 offset:33456
	ds_read_b128 v[80:83], v240 offset:7344
	ds_read_b128 v[88:91], v240 offset:24752
	v_pk_mul_f32 v[226:227], v[206:207], v[106:107] op_sel_hi:[1,0]
	v_pk_mul_f32 v[228:229], v[206:207], v[96:97] op_sel_hi:[1,0]
	v_pk_fma_f32 v[226:227], v[208:209], v[106:107], v[226:227] op_sel:[0,1,0]
	v_pk_fma_f32 v[228:229], v[208:209], v[96:97], v[228:229] op_sel:[0,1,0]
	v_pk_fma_f32 v[226:227], v[210:211], v[108:109], v[226:227] op_sel_hi:[1,0,1]
	v_pk_fma_f32 v[228:229], v[210:211], v[98:99], v[228:229] op_sel_hi:[1,0,1]
	v_pk_fma_f32 v[226:227], v[212:213], v[108:109], v[226:227] op_sel:[0,1,0]
	v_pk_fma_f32 v[228:229], v[212:213], v[98:99], v[228:229] op_sel:[0,1,0]
	v_pk_mul_f32 v[232:233], v[58:59], v[114:115] op_sel_hi:[1,0]
	v_add_f32_dpp v230, v227, v226 row_ror:8 row_mask:0xf bank_mask:0xf
	v_pk_mul_f32 v[234:235], v[58:59], v[114:115] op_sel:[0,1]
	v_pk_mul_f32 v[236:237], v[58:59], v[116:117] op_sel_hi:[1,0]
	v_add_f32_dpp v230, v230, v230 quad_perm:[1,0,3,2] row_mask:0xf bank_mask:0xf
	v_pk_mul_f32 v[238:239], v[58:59], v[116:117] op_sel:[0,1]
	ds_read_b128 v[96:99], v240 offset:41888
	v_add_f32_dpp v230, v230, v230 quad_perm:[2,3,0,1] row_mask:0xf bank_mask:0xf
	v_pk_fma_f32 v[232:233], v[206:207], v[102:103], v[232:233] op_sel_hi:[1,0,1]
	v_pk_fma_f32 v[234:235], v[208:209], v[102:103], v[234:235] op_sel:[0,1,0]
	v_add_f32_dpp v230, v230, v230 row_half_mirror row_mask:0xf bank_mask:0xf
	v_pk_fma_f32 v[236:237], v[210:211], v[104:105], v[236:237] op_sel_hi:[1,0,1]
	v_pk_fma_f32 v[238:239], v[212:213], v[104:105], v[238:239] op_sel:[0,1,0]
	v_mov_b32_dpp v231, v230 row_ror:8 row_mask:0xf bank_mask:0xf
	ds_write_b64 v217, v[228:229] offset:4608
	v_pk_fma_f32 v[206:207], v[110:111], v[230:231], v[232:233] op_sel_hi:[0,1,1] neg_lo:[1,0,0] neg_hi:[1,0,0]
	v_pk_fma_f32 v[208:209], v[110:111], v[230:231], v[234:235] op_sel:[1,0,0] neg_lo:[1,0,0] neg_hi:[1,0,0]
	v_pk_fma_f32 v[210:211], v[112:113], v[230:231], v[236:237] op_sel_hi:[0,1,1] neg_lo:[1,0,0] neg_hi:[1,0,0]
	v_pk_fma_f32 v[212:213], v[112:113], v[230:231], v[238:239] op_sel:[1,0,0] neg_lo:[1,0,0] neg_hi:[1,0,0]
	s_waitcnt lgkmcnt(7)
	ds_read_b128 v[106:109], v240 offset:16320
	ds_read_b128 v[56:59], v242 offset:50912
	ds_read_b128 v[114:117], v240 offset:33728
	ds_read_b128 v[102:105], v240 offset:7616
	ds_read_b128 v[110:113], v240 offset:25024
	v_pk_mul_f32 v[226:227], v[206:207], v[4:5] op_sel_hi:[1,0]
	v_pk_mul_f32 v[228:229], v[206:207], v[222:223] op_sel_hi:[1,0]
	v_pk_fma_f32 v[226:227], v[208:209], v[4:5], v[226:227] op_sel:[0,1,0]
	v_pk_fma_f32 v[228:229], v[208:209], v[222:223], v[228:229] op_sel:[0,1,0]
	v_pk_fma_f32 v[226:227], v[210:211], v[6:7], v[226:227] op_sel_hi:[1,0,1]
	v_pk_fma_f32 v[228:229], v[210:211], v[224:225], v[228:229] op_sel_hi:[1,0,1]
	v_pk_fma_f32 v[226:227], v[212:213], v[6:7], v[226:227] op_sel:[0,1,0]
	v_pk_fma_f32 v[228:229], v[212:213], v[224:225], v[228:229] op_sel:[0,1,0]
	v_pk_mul_f32 v[232:233], v[60:61], v[12:13] op_sel_hi:[1,0]
	v_add_f32_dpp v230, v227, v226 row_ror:8 row_mask:0xf bank_mask:0xf
	v_pk_mul_f32 v[234:235], v[60:61], v[12:13] op_sel:[0,1]
	v_pk_mul_f32 v[236:237], v[60:61], v[14:15] op_sel_hi:[1,0]
	v_add_f32_dpp v230, v230, v230 quad_perm:[1,0,3,2] row_mask:0xf bank_mask:0xf
	v_pk_mul_f32 v[238:239], v[60:61], v[14:15] op_sel:[0,1]
	ds_read_b128 v[222:225], v240 offset:42160
	v_add_f32_dpp v230, v230, v230 quad_perm:[2,3,0,1] row_mask:0xf bank_mask:0xf
	v_pk_fma_f32 v[232:233], v[206:207], v[0:1], v[232:233] op_sel_hi:[1,0,1]
	v_pk_fma_f32 v[234:235], v[208:209], v[0:1], v[234:235] op_sel:[0,1,0]
	v_add_f32_dpp v230, v230, v230 row_half_mirror row_mask:0xf bank_mask:0xf
	v_pk_fma_f32 v[236:237], v[210:211], v[2:3], v[236:237] op_sel_hi:[1,0,1]
	v_pk_fma_f32 v[238:239], v[212:213], v[2:3], v[238:239] op_sel:[0,1,0]
	v_mov_b32_dpp v231, v230 row_ror:8 row_mask:0xf bank_mask:0xf
	ds_write_b64 v217, v[228:229] offset:5184
	v_pk_fma_f32 v[206:207], v[8:9], v[230:231], v[232:233] op_sel_hi:[0,1,1] neg_lo:[1,0,0] neg_hi:[1,0,0]
	v_pk_fma_f32 v[208:209], v[8:9], v[230:231], v[234:235] op_sel:[1,0,0] neg_lo:[1,0,0] neg_hi:[1,0,0]
	v_pk_fma_f32 v[210:211], v[10:11], v[230:231], v[236:237] op_sel_hi:[0,1,1] neg_lo:[1,0,0] neg_hi:[1,0,0]
	v_pk_fma_f32 v[212:213], v[10:11], v[230:231], v[238:239] op_sel:[1,0,0] neg_lo:[1,0,0] neg_hi:[1,0,0]
	s_waitcnt lgkmcnt(8)
; template <int CTRL> __device__ __forceinline__ float dppf(float x) { return __builtin_bit_cast(float, __builtin_amdgcn_update_dpp(0, __builtin_bit_cast(int, x), CTRL, 0xF, 0xF, false)); }
; __device__ __forceinline__ void phase_rwkv_scan(const Fr& F, int jr) {
;     ...
;                         const int p = pg + pi, pn = p < 63 ? p + 1 : 63;
;                         const f32x4 w4n = PW[pn * 16], k4n = PW[1024 + pn * 16], b4n = PW[2048 + pn * 16], d4n = PW[3072 + pn * 16], r4n = PR[pn * 16];
;                         const float vvn = PV[pn * 32];
;                         f32x2 t = S01 * k4.xy; t = S23 * k4.zw + t; float sa = t.x + t.y;
;                         sa += dppf<0x128>(sa);
;                         const f32x2 dv01 = d4.xy * vv, dv23 = d4.zw * vv;
;                         sa += dppf<0x124>(sa);
;                         const f32x2 e01 = S01 * w4.xy + dv01;
;                         sa += dppf<0x122>(sa);
;                         const f32x2 e23 = S23 * w4.zw + dv23;
;                         sa += dppf<0x121>(sa);
;                         S01 = e01 - b4.xy * sa; S23 = e23 - b4.zw * sa;
;                         f32x2 u = S01 * r4.xy; u = S23 * r4.zw + u;
;                         PY[pi * 64] = u.x + u.y;
;                         w4 = w4n; k4 = k4n; b4 = b4n; d4 = d4n; r4 = r4n; vv = vvn;
	ds_read_b128 v[4:7], v240 offset:16592
	ds_read_b128 v[12:15], v240 offset:34000
	ds_read_b128 v[0:3], v240 offset:7888
	ds_read_b128 v[8:11], v240 offset:25296
	v_pk_mul_f32 v[226:227], v[206:207], v[84:85] op_sel_hi:[1,0]
	v_pk_mul_f32 v[228:229], v[206:207], v[96:97] op_sel_hi:[1,0]
	v_pk_fma_f32 v[226:227], v[208:209], v[84:85], v[226:227] op_sel:[0,1,0]
	v_pk_fma_f32 v[228:229], v[208:209], v[96:97], v[228:229] op_sel:[0,1,0]
	v_pk_fma_f32 v[226:227], v[210:211], v[86:87], v[226:227] op_sel_hi:[1,0,1]
	v_pk_fma_f32 v[228:229], v[210:211], v[98:99], v[228:229] op_sel_hi:[1,0,1]
	v_pk_fma_f32 v[226:227], v[212:213], v[86:87], v[226:227] op_sel:[0,1,0]
	v_pk_fma_f32 v[228:229], v[212:213], v[98:99], v[228:229] op_sel:[0,1,0]
	v_pk_mul_f32 v[232:233], v[62:63], v[92:93] op_sel_hi:[1,0]
	v_add_f32_dpp v230, v227, v226 row_ror:8 row_mask:0xf bank_mask:0xf
	v_pk_mul_f32 v[234:235], v[62:63], v[92:93] op_sel:[0,1]
	v_pk_mul_f32 v[236:237], v[62:63], v[94:95] op_sel_hi:[1,0]
	v_add_f32_dpp v230, v230, v230 quad_perm:[1,0,3,2] row_mask:0xf bank_mask:0xf
	v_pk_mul_f32 v[238:239], v[62:63], v[94:95] op_sel:[0,1]
	ds_read_b128 v[96:99], v240 offset:42432
	v_add_f32_dpp v230, v230, v230 quad_perm:[2,3,0,1] row_mask:0xf bank_mask:0xf
	v_pk_fma_f32 v[232:233], v[206:207], v[80:81], v[232:233] op_sel_hi:[1,0,1]
	v_pk_fma_f32 v[234:235], v[208:209], v[80:81], v[234:235] op_sel:[0,1,0]
	v_add_f32_dpp v230, v230, v230 row_half_mirror row_mask:0xf bank_mask:0xf
	v_pk_fma_f32 v[236:237], v[210:211], v[82:83], v[236:237] op_sel_hi:[1,0,1]
	v_pk_fma_f32 v[238:239], v[212:213], v[82:83], v[238:239] op_sel:[0,1,0]
	v_mov_b32_dpp v231, v230 row_ror:8 row_mask:0xf bank_mask:0xf
	ds_write_b64 v217, v[228:229] offset:5760
	v_pk_fma_f32 v[206:207], v[88:89], v[230:231], v[232:233] op_sel_hi:[0,1,1] neg_lo:[1,0,0] neg_hi:[1,0,0]
	v_pk_fma_f32 v[208:209], v[88:89], v[230:231], v[234:235] op_sel:[1,0,0] neg_lo:[1,0,0] neg_hi:[1,0,0]
	v_pk_fma_f32 v[210:211], v[90:91], v[230:231], v[236:237] op_sel_hi:[0,1,1] neg_lo:[1,0,0] neg_hi:[1,0,0]
	v_pk_fma_f32 v[212:213], v[90:91], v[230:231], v[238:239] op_sel:[1,0,0] neg_lo:[1,0,0] neg_hi:[1,0,0]
	s_waitcnt lgkmcnt(7)
	ds_read_b128 v[84:87], v240 offset:16864
	ds_read_b128 v[60:63], v242 offset:51440
	ds_read_b128 v[92:95], v240 offset:34272
	ds_read_b128 v[80:83], v240 offset:8160
	ds_read_b128 v[88:91], v240 offset:25568
	v_pk_mul_f32 v[226:227], v[206:207], v[106:107] op_sel_hi:[1,0]
	v_pk_mul_f32 v[228:229], v[206:207], v[222:223] op_sel_hi:[1,0]
	v_pk_fma_f32 v[226:227], v[208:209], v[106:107], v[226:227] op_sel:[0,1,0]
	v_pk_fma_f32 v[228:229], v[208:209], v[222:223], v[228:229] op_sel:[0,1,0]
	v_pk_fma_f32 v[226:227], v[210:211], v[108:109], v[226:227] op_sel_hi:[1,0,1]
	v_pk_fma_f32 v[228:229], v[210:211], v[224:225], v[228:229] op_sel_hi:[1,0,1]
	v_pk_fma_f32 v[226:227], v[212:213], v[108:109], v[226:227] op_sel:[0,1,0]
	v_pk_fma_f32 v[228:229], v[212:213], v[224:225], v[228:229] op_sel:[0,1,0]
	v_pk_mul_f32 v[232:233], v[56:57], v[114:115] op_sel_hi:[1,0]
	v_add_f32_dpp v230, v227, v226 row_ror:8 row_mask:0xf bank_mask:0xf
	v_pk_mul_f32 v[234:235], v[56:57], v[114:115] op_sel:[0,1]
	v_pk_mul_f32 v[236:237], v[56:57], v[116:117] op_sel_hi:[1,0]
	v_add_f32_dpp v230, v230, v230 quad_perm:[1,0,3,2] row_mask:0xf bank_mask:0xf
	v_pk_mul_f32 v[238:239], v[56:57], v[116:117] op_sel:[0,1]
	ds_read_b128 v[222:225], v240 offset:42704
	v_add_f32_dpp v230, v230, v230 quad_perm:[2,3,0,1] row_mask:0xf bank_mask:0xf
	v_pk_fma_f32 v[232:233], v[206:207], v[102:103], v[232:233] op_sel_hi:[1,0,1]
	v_pk_fma_f32 v[234:235], v[208:209], v[102:103], v[234:235] op_sel:[0,1,0]
	v_add_f32_dpp v230, v230, v230 row_half_mirror row_mask:0xf bank_mask:0xf
	v_pk_fma_f32 v[236:237], v[210:211], v[104:105], v[236:237] op_sel_hi:[1,0,1]
	v_pk_fma_f32 v[238:239], v[212:213], v[104:105], v[238:239] op_sel:[0,1,0]
	v_mov_b32_dpp v231, v230 row_ror:8 row_mask:0xf bank_mask:0xf
	ds_write_b64 v217, v[228:229] offset:6336
	v_pk_fma_f32 v[206:207], v[110:111], v[230:231], v[232:233] op_sel_hi:[0,1,1] neg_lo:[1,0,0] neg_hi:[1,0,0]
	v_pk_fma_f32 v[208:209], v[110:111], v[230:231], v[234:235] op_sel:[1,0,0] neg_lo:[1,0,0] neg_hi:[1,0,0]
	v_pk_fma_f32 v[210:211], v[112:113], v[230:231], v[236:237] op_sel_hi:[0,1,1] neg_lo:[1,0,0] neg_hi:[1,0,0]
	v_pk_fma_f32 v[212:213], v[112:113], v[230:231], v[238:239] op_sel:[1,0,0] neg_lo:[1,0,0] neg_hi:[1,0,0]
	s_waitcnt lgkmcnt(8)
	ds_read_b128 v[106:109], v240 offset:17136
	ds_read_b128 v[114:117], v240 offset:34544
	ds_read_b128 v[102:105], v240 offset:8432
	ds_read_b128 v[110:113], v240 offset:25840
	v_pk_mul_f32 v[226:227], v[206:207], v[4:5] op_sel_hi:[1,0]
	v_pk_mul_f32 v[228:229], v[206:207], v[96:97] op_sel_hi:[1,0]
	v_pk_fma_f32 v[226:227], v[208:209], v[4:5], v[226:227] op_sel:[0,1,0]
	v_pk_fma_f32 v[228:229], v[208:209], v[96:97], v[228:229] op_sel:[0,1,0]
	v_pk_fma_f32 v[226:227], v[210:211], v[6:7], v[226:227] op_sel_hi:[1,0,1]
	v_pk_fma_f32 v[228:229], v[210:211], v[98:99], v[228:229] op_sel_hi:[1,0,1]
	v_pk_fma_f32 v[226:227], v[212:213], v[6:7], v[226:227] op_sel:[0,1,0]
	v_pk_fma_f32 v[228:229], v[212:213], v[98:99], v[228:229] op_sel:[0,1,0]
	v_pk_mul_f32 v[232:233], v[58:59], v[12:13] op_sel_hi:[1,0]
	v_add_f32_dpp v230, v227, v226 row_ror:8 row_mask:0xf bank_mask:0xf
	v_pk_mul_f32 v[234:235], v[58:59], v[12:13] op_sel:[0,1]
	v_pk_mul_f32 v[236:237], v[58:59], v[14:15] op_sel_hi:[1,0]
	v_add_f32_dpp v230, v230, v230 quad_perm:[1,0,3,2] row_mask:0xf bank_mask:0xf
	v_pk_mul_f32 v[238:239], v[58:59], v[14:15] op_sel:[0,1]
	ds_read_b128 v[96:99], v240 offset:42976
	v_add_f32_dpp v230, v230, v230 quad_perm:[2,3,0,1] row_mask:0xf bank_mask:0xf
	v_pk_fma_f32 v[232:233], v[206:207], v[0:1], v[232:233] op_sel_hi:[1,0,1]
	v_pk_fma_f32 v[234:235], v[208:209], v[0:1], v[234:235] op_sel:[0,1,0]
	v_add_f32_dpp v230, v230, v230 row_half_mirror row_mask:0xf bank_mask:0xf
	v_pk_fma_f32 v[236:237], v[210:211], v[2:3], v[236:237] op_sel_hi:[1,0,1]
	v_pk_fma_f32 v[238:239], v[212:213], v[2:3], v[238:239] op_sel:[0,1,0]
	v_mov_b32_dpp v231, v230 row_ror:8 row_mask:0xf bank_mask:0xf
	ds_write_b64 v217, v[228:229] offset:6912
	v_pk_fma_f32 v[206:207], v[8:9], v[230:231], v[232:233] op_sel_hi:[0,1,1] neg_lo:[1,0,0] neg_hi:[1,0,0]
	v_pk_fma_f32 v[208:209], v[8:9], v[230:231], v[234:235] op_sel:[1,0,0] neg_lo:[1,0,0] neg_hi:[1,0,0]
	v_pk_fma_f32 v[210:211], v[10:11], v[230:231], v[236:237] op_sel_hi:[0,1,1] neg_lo:[1,0,0] neg_hi:[1,0,0]
	v_pk_fma_f32 v[212:213], v[10:11], v[230:231], v[238:239] op_sel:[1,0,0] neg_lo:[1,0,0] neg_hi:[1,0,0]
	s_waitcnt lgkmcnt(7)
; __device__ __forceinline__ unsigned f2bf(float f) { unsigned u = __builtin_bit_cast(unsigned, f); return (u + 0x7fffu + ((u >> 16) & 1u)) >> 16; }
; template <int CTRL> __device__ __forceinline__ float dppf(float x) { return __builtin_bit_cast(float, __builtin_amdgcn_update_dpp(0, __builtin_bit_cast(int, x), CTRL, 0xF, 0xF, false)); }
; __device__ __forceinline__ void phase_rwkv_scan(const Fr& F, int jr) {
;     ...
;                         const int p = pg + pi, pn = p < 63 ? p + 1 : 63;
;                         const f32x4 w4n = PW[pn * 16], k4n = PW[1024 + pn * 16], b4n = PW[2048 + pn * 16], d4n = PW[3072 + pn * 16], r4n = PR[pn * 16];
;                         const float vvn = PV[pn * 32];
;                         f32x2 t = S01 * k4.xy; t = S23 * k4.zw + t; float sa = t.x + t.y;
;                         sa += dppf<0x128>(sa);
;                         const f32x2 dv01 = d4.xy * vv, dv23 = d4.zw * vv;
;                         sa += dppf<0x124>(sa);
;                         const f32x2 e01 = S01 * w4.xy + dv01;
;                         sa += dppf<0x122>(sa);
;                         const f32x2 e23 = S23 * w4.zw + dv23;
;                         sa += dppf<0x121>(sa);
;                         S01 = e01 - b4.xy * sa; S23 = e23 - b4.zw * sa;
;                         f32x2 u = S01 * r4.xy; u = S23 * r4.zw + u;
;                         PY[pi * 64] = u.x + u.y;
;                         w4 = w4n; k4 = k4n; b4 = b4n; d4 = d4n; r4 = r4n; vv = vvn;
;                     }
;                     asm volatile("s_waitcnt lgkmcnt(0)" ::: "memory");
;                     {
;                         const int j = lane >> 2, q = lane & 3; const float* yp = Ypw + j * 64 + q * 16;
;                         const f32x4 a0 = *(const f32x4*)yp, a1 = *(const f32x4*)(yp + 4), a2 = *(const f32x4*)(yp + 8), a3 = *(const f32x4*)(yp + 12);
;                         const f32x4 ssum = (a0 + a1) + (a2 + a3); const float yv = (ssum.x + ssum.y) + (ssum.z + ssum.w);
;                         const size_t row = (size_t)b * TB + tokof(s, chunk * 64 + pg + j);
;                         Yb[row * D + h * 64 + 32 * half + 4 * wave + q] = (bf16)f2bf(yv);
;                     }
;                     asm volatile("s_waitcnt lgkmcnt(0)" ::: "memory");
;                 }
;             }
;             LDS_BAR();
;         }
	v_pk_mul_f32 v[226:227], v[206:207], v[84:85] op_sel_hi:[1,0]
	v_pk_mul_f32 v[228:229], v[206:207], v[222:223] op_sel_hi:[1,0]
	v_pk_fma_f32 v[226:227], v[208:209], v[84:85], v[226:227] op_sel:[0,1,0]
	v_pk_fma_f32 v[228:229], v[208:209], v[222:223], v[228:229] op_sel:[0,1,0]
	v_pk_fma_f32 v[226:227], v[210:211], v[86:87], v[226:227] op_sel_hi:[1,0,1]
	v_pk_fma_f32 v[228:229], v[210:211], v[224:225], v[228:229] op_sel_hi:[1,0,1]
	v_pk_fma_f32 v[226:227], v[212:213], v[86:87], v[226:227] op_sel:[0,1,0]
	v_pk_fma_f32 v[228:229], v[212:213], v[224:225], v[228:229] op_sel:[0,1,0]
	v_pk_mul_f32 v[232:233], v[60:61], v[92:93] op_sel_hi:[1,0]
	v_add_f32_dpp v230, v227, v226 row_ror:8 row_mask:0xf bank_mask:0xf
	v_pk_mul_f32 v[234:235], v[60:61], v[92:93] op_sel:[0,1]
	v_pk_mul_f32 v[236:237], v[60:61], v[94:95] op_sel_hi:[1,0]
	v_add_f32_dpp v230, v230, v230 quad_perm:[1,0,3,2] row_mask:0xf bank_mask:0xf
	v_pk_mul_f32 v[238:239], v[60:61], v[94:95] op_sel:[0,1]
	ds_read_b128 v[222:225], v240 offset:43248
	v_add_f32_dpp v230, v230, v230 quad_perm:[2,3,0,1] row_mask:0xf bank_mask:0xf
	v_pk_fma_f32 v[232:233], v[206:207], v[80:81], v[232:233] op_sel_hi:[1,0,1]
	v_pk_fma_f32 v[234:235], v[208:209], v[80:81], v[234:235] op_sel:[0,1,0]
	v_add_f32_dpp v230, v230, v230 row_half_mirror row_mask:0xf bank_mask:0xf
	v_pk_fma_f32 v[236:237], v[210:211], v[82:83], v[236:237] op_sel_hi:[1,0,1]
	v_pk_fma_f32 v[238:239], v[212:213], v[82:83], v[238:239] op_sel:[0,1,0]
	v_mov_b32_dpp v231, v230 row_ror:8 row_mask:0xf bank_mask:0xf
	ds_write_b64 v217, v[228:229] offset:7488
	v_pk_fma_f32 v[206:207], v[88:89], v[230:231], v[232:233] op_sel_hi:[0,1,1] neg_lo:[1,0,0] neg_hi:[1,0,0]
	v_pk_fma_f32 v[208:209], v[88:89], v[230:231], v[234:235] op_sel:[1,0,0] neg_lo:[1,0,0] neg_hi:[1,0,0]
	v_pk_fma_f32 v[210:211], v[90:91], v[230:231], v[236:237] op_sel_hi:[0,1,1] neg_lo:[1,0,0] neg_hi:[1,0,0]
	v_pk_fma_f32 v[212:213], v[90:91], v[230:231], v[238:239] op_sel:[1,0,0] neg_lo:[1,0,0] neg_hi:[1,0,0]
	s_waitcnt lgkmcnt(3)
	v_pk_mul_f32 v[226:227], v[206:207], v[106:107] op_sel_hi:[1,0]
	v_pk_mul_f32 v[228:229], v[206:207], v[96:97] op_sel_hi:[1,0]
	v_pk_fma_f32 v[226:227], v[208:209], v[106:107], v[226:227] op_sel:[0,1,0]
	v_pk_fma_f32 v[228:229], v[208:209], v[96:97], v[228:229] op_sel:[0,1,0]
	v_pk_fma_f32 v[226:227], v[210:211], v[108:109], v[226:227] op_sel_hi:[1,0,1]
	v_pk_fma_f32 v[228:229], v[210:211], v[98:99], v[228:229] op_sel_hi:[1,0,1]
	v_pk_fma_f32 v[226:227], v[212:213], v[108:109], v[226:227] op_sel:[0,1,0]
	v_pk_fma_f32 v[228:229], v[212:213], v[98:99], v[228:229] op_sel:[0,1,0]
	v_pk_mul_f32 v[232:233], v[62:63], v[114:115] op_sel_hi:[1,0]
	v_add_f32_dpp v230, v227, v226 row_ror:8 row_mask:0xf bank_mask:0xf
	v_pk_mul_f32 v[234:235], v[62:63], v[114:115] op_sel:[0,1]
	v_pk_mul_f32 v[236:237], v[62:63], v[116:117] op_sel_hi:[1,0]
	v_add_f32_dpp v230, v230, v230 quad_perm:[1,0,3,2] row_mask:0xf bank_mask:0xf
	v_pk_mul_f32 v[238:239], v[62:63], v[116:117] op_sel:[0,1]
	s_nop 0
	v_add_f32_dpp v230, v230, v230 quad_perm:[2,3,0,1] row_mask:0xf bank_mask:0xf
	v_pk_fma_f32 v[232:233], v[206:207], v[102:103], v[232:233] op_sel_hi:[1,0,1]
	v_pk_fma_f32 v[234:235], v[208:209], v[102:103], v[234:235] op_sel:[0,1,0]
	v_add_f32_dpp v230, v230, v230 row_half_mirror row_mask:0xf bank_mask:0xf
	v_pk_fma_f32 v[236:237], v[210:211], v[104:105], v[236:237] op_sel_hi:[1,0,1]
	v_pk_fma_f32 v[238:239], v[212:213], v[104:105], v[238:239] op_sel:[0,1,0]
	v_mov_b32_dpp v231, v230 row_ror:8 row_mask:0xf bank_mask:0xf
	ds_write_b64 v217, v[228:229] offset:8064
	v_pk_fma_f32 v[206:207], v[110:111], v[230:231], v[232:233] op_sel_hi:[0,1,1] neg_lo:[1,0,0] neg_hi:[1,0,0]
	v_pk_fma_f32 v[208:209], v[110:111], v[230:231], v[234:235] op_sel:[1,0,0] neg_lo:[1,0,0] neg_hi:[1,0,0]
	v_pk_fma_f32 v[210:211], v[112:113], v[230:231], v[236:237] op_sel_hi:[0,1,1] neg_lo:[1,0,0] neg_hi:[1,0,0]
	v_pk_fma_f32 v[212:213], v[112:113], v[230:231], v[238:239] op_sel:[1,0,0] neg_lo:[1,0,0] neg_hi:[1,0,0]
	s_waitcnt lgkmcnt(2)
	v_pk_mul_f32 v[228:229], v[206:207], v[222:223] op_sel_hi:[1,0]
	v_add_u32_e32 v243, s15, v219
	v_pk_fma_f32 v[228:229], v[208:209], v[222:223], v[228:229] op_sel:[0,1,0]
	v_lshl_add_u32 v243, v243, 11, v220
	v_pk_fma_f32 v[228:229], v[210:211], v[224:225], v[228:229] op_sel_hi:[1,0,1]
	v_pk_fma_f32 v[228:229], v[212:213], v[224:225], v[228:229] op_sel:[0,1,0]
	s_waitcnt lgkmcnt(1)
	ds_write_b64 v217, v[228:229] offset:8640
	ds_read_b128 v[24:27], v218 offset:0
	ds_read_b128 v[28:31], v218 offset:16
	ds_read_b128 v[32:35], v218 offset:32
	ds_read_b128 v[36:39], v218 offset:48
	ds_read_b128 v[40:43], v218 offset:64
	ds_read_b128 v[44:47], v218 offset:80
	ds_read_b128 v[48:51], v218 offset:96
	ds_read_b128 v[52:55], v218 offset:112
	s_waitcnt lgkmcnt(4)
	v_pk_add_f32 v[24:25], v[24:25], v[26:27]
	v_pk_add_f32 v[28:29], v[28:29], v[30:31]
	v_pk_add_f32 v[32:33], v[32:33], v[34:35]
	v_pk_add_f32 v[36:37], v[36:37], v[38:39]
	v_pk_add_f32 v[24:25], v[24:25], v[28:29]
	s_waitcnt lgkmcnt(0)
	v_pk_add_f32 v[40:41], v[40:41], v[42:43]
	v_pk_add_f32 v[44:45], v[44:45], v[46:47]
	v_pk_add_f32 v[32:33], v[32:33], v[36:37]
	v_pk_add_f32 v[48:49], v[48:49], v[50:51]
	v_pk_add_f32 v[52:53], v[52:53], v[54:55]
	v_pk_add_f32 v[40:41], v[40:41], v[44:45]
	v_pk_add_f32 v[24:25], v[24:25], v[32:33]
	v_pk_add_f32 v[48:49], v[48:49], v[52:53]
	s_add_i32 s15, s15, s19
	v_pk_add_f32 v[40:41], v[40:41], v[48:49]
	v_pk_add_f32 v[24:25], v[24:25], v[40:41] op_sel:[0,1] op_sel_hi:[1,0]
	v_cvt_pk_bf16_f32 v244, v24, v25
	global_store_dword v243, v244, s[20:21]
	s_waitcnt lgkmcnt(0)
	s_add_i32 s10, s10, 1
	s_xor_b32 s11, s11, 0xcc00
	s_cmp_eq_u32 s10, 8
	s_cselect_b32 s17, s18, 0
	s_add_i32 s15, s15, s17
	s_barrier
	s_cmp_lt_u32 s10, 136
	s_cbranch_scc1 .Lrw0_shc
	s_setprio 0
	s_branch .Lrw0_end
